# attention phase: ONE static s_setprio 1 for waves 4-7 at phase entry, all per-section priority flips deleted
# baseline (speedup 1.0000x reference)
.LBB0_312:
	s_andn2_b64 vcc, exec, s[0:1]
	s_cbranch_vccnz .LBB0_528
	v_readlane_b32 s0, v254, 53
	v_readlane_b32 s1, v254, 54
	v_mov_b32_e32 v2, v206
	v_readlane_b32 s36, v252, 33
	v_cndmask_b32_e64 v0, 0, 1, s[0:1]
	v_lshlrev_b32_e32 v0, 2, v0
	v_lshl_add_u64 v[146:147], s[26:27], 0, v[0:1]
	v_ashrrev_i32_e32 v0, 3, v2
	v_ashrrev_i32_e32 v164, 6, v2
	v_and_b32_e32 v3, 63, v2
	v_and_b32_e32 v167, 0xffffffe0, v0
	v_mov_b32_e32 v0, 0xfffed000
	v_lshl_add_u32 v171, v164, 3, v0
	v_lshlrev_b32_e32 v0, 2, v3
	v_readlane_b32 s37, v252, 34
	v_readlane_b32 s38, v252, 35
	v_readlane_b32 s39, v252, 36
	v_readlane_b32 s40, v252, 37
	v_readlane_b32 s41, v252, 38
	v_readlane_b32 s42, v252, 39
	v_readlane_b32 s43, v252, 40
	v_readlane_b32 s44, v252, 41
	v_readlane_b32 s45, v252, 42
	v_readlane_b32 s46, v252, 43
	v_readlane_b32 s47, v252, 44
	v_readlane_b32 s48, v252, 45
	v_readlane_b32 s49, v252, 46
	v_readlane_b32 s50, v252, 47
	v_readlane_b32 s51, v252, 48
	v_lshlrev_b32_e32 v4, 11, v164
	v_lshl_add_u64 v[148:149], s[38:39], 0, v[0:1]
	v_readlane_b32 s36, v253, 33
	v_cmp_eq_u32_e64 s[72:73], 0, v2
	s_and_b64 s[0:1], s[0:1], exec
	v_lshlrev_b32_e32 v168, 5, v164
	v_ashrrev_i32_e32 v169, 7, v2
	v_or_b32_e32 v2, v4, v0
	v_lshlrev_b32_e32 v0, 4, v3
	v_readlane_b32 s46, v253, 43
	v_readlane_b32 s47, v253, 44
	v_add_u32_e32 v165, 0x18000, v4
	v_and_b32_e32 v166, 3, v164
	s_cselect_b32 s3, 8, 0
	v_and_b32_e32 v170, 32, v168
	v_cmp_eq_u32_e64 s[6:7], 0, v3
	v_or_b32_e32 v172, 0xffffffc0, v3
	v_add_u32_e32 v173, 0x18000, v2
	v_lshlrev_b16_e32 v174, 3, v164
	v_lshl_add_u64 v[150:151], s[46:47], 0, v[0:1]
	v_readlane_b32 s37, v253, 34
	v_readlane_b32 s38, v253, 35
	v_readlane_b32 s39, v253, 36
	v_readlane_b32 s40, v253, 37
	v_readlane_b32 s41, v253, 38
	v_readlane_b32 s42, v253, 39
	v_readlane_b32 s43, v253, 40
	v_readlane_b32 s44, v253, 41
	v_readlane_b32 s45, v253, 42
	v_readlane_b32 s48, v253, 45
	v_readlane_b32 s49, v253, 46
	v_readlane_b32 s50, v253, 47
	v_readlane_b32 s51, v253, 48
	v_readfirstlane_b32 s0, v206
	s_nop 3
	s_cmp_ge_u32 s0, 0x100
	s_cbranch_scc0 .Lprio_static
	s_setprio 1
.Lprio_static:
	s_branch .LBB0_316
.LBB0_314:
	s_mov_b64 s[0:1], 0

.LBB0_340:
	v_add_u32_e32 v101, s4, v96
	v_add_u32_e32 v100, s4, v95
	v_add_u32_e32 v99, s4, v94
	v_add_u32_e32 v98, s4, v93
	ds_read_b128 v[196:199], v101
	ds_read_b128 v[200:203], v100
	ds_read_b128 v[232:235], v101 offset:4096
	ds_read_b128 v[236:239], v100 offset:4096
	ds_read_b128 v[240:243], v99
	s_waitcnt lgkmcnt(4)
	v_mfma_f32_32x32x16_bf16 v[34:49], v[196:199], v[66:69], 0
	ds_read_b128 v[244:247], v99 offset:4096
	s_waitcnt lgkmcnt(4)
	v_mfma_f32_32x32x16_bf16 v[34:49], v[200:203], v[70:73], v[34:49]
	ds_read_b128 v[196:199], v98 offset:4096
	s_waitcnt lgkmcnt(4)
	v_mfma_f32_32x32x16_bf16 v[50:65], v[232:235], v[66:69], 0
	ds_read_b128 v[200:203], v98
	s_waitcnt lgkmcnt(4)
	v_mfma_f32_32x32x16_bf16 v[50:65], v[236:239], v[70:73], v[50:65]
	s_waitcnt lgkmcnt(3)
	v_mfma_f32_32x32x16_bf16 v[34:49], v[240:243], v[74:77], v[34:49]
	s_waitcnt lgkmcnt(2)
	v_mfma_f32_32x32x16_bf16 v[50:65], v[244:247], v[74:77], v[50:65]
	s_waitcnt lgkmcnt(1)
	v_mfma_f32_32x32x16_bf16 v[50:65], v[196:199], v[78:81], v[50:65]
	s_waitcnt lgkmcnt(0)
	v_mfma_f32_32x32x16_bf16 v[34:49], v[200:203], v[78:81], v[34:49]
	s_nop 1
	s_nop 8
	s_nop 7
	s_nop 4
	v_max3_f32 v0, v50, v51, v52
	v_max3_f32 v97, v34, v35, v36
	v_max3_f32 v0, v0, v53, v54
	v_max3_f32 v97, v97, v37, v38
	v_max3_f32 v0, v0, v55, v56
	v_max3_f32 v97, v97, v39, v40
	v_max3_f32 v0, v0, v57, v58
	v_max3_f32 v97, v97, v41, v42
	v_max3_f32 v0, v0, v59, v60
	v_max3_f32 v97, v97, v43, v44
	v_max3_f32 v0, v0, v61, v62
	v_max3_f32 v97, v97, v45, v46
	v_max3_f32 v0, v0, v63, v64
	v_max3_f32 v97, v97, v47, v48
	v_max3_f32 v97, v97, v49, v65
	v_max_f32_e32 v0, v0, v97
	v_and_b32_e32 v104, 64, v221
	v_xor_b32_e32 v97, 32, v221
	v_add_u32_e32 v104, 64, v104
	v_cmp_lt_i32_e32 vcc, v97, v104
	s_nop 1
	v_cndmask_b32_e32 v97, v221, v97, vcc
	v_lshlrev_b32_e32 v104, 2, v97
	ds_bpermute_b32 v97, v104, v0
	s_waitcnt lgkmcnt(0)
	v_max3_f32 v97, v103, v0, v97
	v_sub_f32_e32 v0, v34, v97
	v_exp_f32_e32 v34, v0
	v_sub_f32_e32 v0, v50, v97
	v_exp_f32_e32 v50, v0
	v_sub_f32_e32 v0, v35, v97
	v_exp_f32_e32 v35, v0
	v_sub_f32_e32 v0, v51, v97
	v_exp_f32_e32 v51, v0
	v_sub_f32_e32 v36, v36, v97
	v_sub_f32_e32 v52, v52, v97
	v_exp_f32_e32 v36, v36
	v_exp_f32_e32 v52, v52
	v_sub_f32_e32 v0, v103, v97
	v_add_f32_e32 v103, v34, v50
	v_add_f32_e32 v103, 0, v103
	v_add_f32_e32 v105, v35, v51
	v_add_f32_e32 v103, v105, v103
	v_add_f32_e32 v105, v36, v52
	v_sub_f32_e32 v38, v38, v97
	v_sub_f32_e32 v37, v37, v97
	v_sub_f32_e32 v53, v53, v97
	v_add_f32_e32 v105, v105, v103
	v_exp_f32_e32 v103, v38
	v_sub_f32_e32 v38, v54, v97
	v_exp_f32_e32 v37, v37
	v_exp_f32_e32 v53, v53
	v_exp_f32_e32 v54, v38
	v_sub_f32_e32 v38, v39, v97
	v_exp_f32_e32 v39, v38
	v_sub_f32_e32 v38, v55, v97
	v_exp_f32_e32 v55, v38
	v_sub_f32_e32 v40, v40, v97
	v_sub_f32_e32 v56, v56, v97
	v_exp_f32_e32 v40, v40
	v_exp_f32_e32 v56, v56
	v_sub_f32_e32 v41, v41, v97
	v_sub_f32_e32 v57, v57, v97
	v_add_f32_e32 v106, v37, v53
	v_exp_f32_e32 v41, v41
	v_exp_f32_e32 v57, v57
	v_sub_f32_e32 v42, v42, v97
	v_sub_f32_e32 v58, v58, v97
	v_add_f32_e32 v38, v106, v105
	v_add_f32_e32 v105, v103, v54
	v_exp_f32_e32 v42, v42
	v_exp_f32_e32 v58, v58
	v_sub_f32_e32 v43, v43, v97
	v_sub_f32_e32 v59, v59, v97
	v_add_f32_e32 v38, v105, v38
	v_add_f32_e32 v105, v39, v55
	v_exp_f32_e32 v43, v43
	v_exp_f32_e32 v59, v59
	v_sub_f32_e32 v44, v44, v97
	v_sub_f32_e32 v60, v60, v97
	v_add_f32_e32 v38, v105, v38
	v_add_f32_e32 v105, v40, v56
	v_exp_f32_e32 v44, v44
	v_exp_f32_e32 v60, v60
	v_sub_f32_e32 v45, v45, v97
	v_sub_f32_e32 v61, v61, v97
	v_add_f32_e32 v38, v105, v38
	v_add_f32_e32 v105, v41, v57
	v_exp_f32_e32 v45, v45
	v_exp_f32_e32 v61, v61
	v_sub_f32_e32 v46, v46, v97
	v_sub_f32_e32 v62, v62, v97
	v_add_f32_e32 v38, v105, v38
	v_add_f32_e32 v105, v42, v58
	v_exp_f32_e32 v46, v46
	v_exp_f32_e32 v62, v62
	v_sub_f32_e32 v47, v47, v97
	v_sub_f32_e32 v63, v63, v97
	v_add_f32_e32 v38, v105, v38
	v_add_f32_e32 v105, v43, v59
	v_exp_f32_e32 v47, v47
	v_exp_f32_e32 v63, v63
	v_sub_f32_e32 v48, v48, v97
	v_sub_f32_e32 v64, v64, v97
	v_add_f32_e32 v38, v105, v38
	v_add_f32_e32 v105, v44, v60
	v_exp_f32_e32 v48, v48
	v_exp_f32_e32 v64, v64
	v_sub_f32_e32 v49, v49, v97
	v_sub_f32_e32 v65, v65, v97
	v_add_f32_e32 v38, v105, v38
	v_add_f32_e32 v105, v45, v61
	v_exp_f32_e32 v49, v49
	v_exp_f32_e32 v65, v65
	v_add_f32_e32 v38, v105, v38
	v_add_f32_e32 v105, v46, v62
	v_add_f32_e32 v38, v105, v38
	v_add_f32_e32 v105, v47, v63
	v_add_f32_e32 v38, v105, v38
	v_add_f32_e32 v105, v48, v64
	v_add_f32_e32 v38, v105, v38
	v_add_f32_e32 v105, v49, v65
	v_add_f32_e32 v38, v105, v38
	v_exp_f32_e32 v0, v0
	ds_bpermute_b32 v104, v104, v38
	v_cmp_neq_f32_e32 vcc, 1.0, v0
	s_cbranch_vccz .LBB0_342
	v_pk_mul_f32 v[32:33], v[32:33], v[0:1] op_sel_hi:[1,0]
	v_pk_mul_f32 v[30:31], v[30:31], v[0:1] op_sel_hi:[1,0]
	v_pk_mul_f32 v[28:29], v[28:29], v[0:1] op_sel_hi:[1,0]
	v_pk_mul_f32 v[26:27], v[26:27], v[0:1] op_sel_hi:[1,0]
	v_pk_mul_f32 v[24:25], v[24:25], v[0:1] op_sel_hi:[1,0]
	v_pk_mul_f32 v[22:23], v[22:23], v[0:1] op_sel_hi:[1,0]
	v_pk_mul_f32 v[20:21], v[20:21], v[0:1] op_sel_hi:[1,0]
	v_pk_mul_f32 v[18:19], v[18:19], v[0:1] op_sel_hi:[1,0]
	v_pk_mul_f32 v[16:17], v[16:17], v[0:1] op_sel_hi:[1,0]
	v_pk_mul_f32 v[14:15], v[14:15], v[0:1] op_sel_hi:[1,0]
	v_pk_mul_f32 v[12:13], v[12:13], v[0:1] op_sel_hi:[1,0]
	v_pk_mul_f32 v[10:11], v[10:11], v[0:1] op_sel_hi:[1,0]
	v_pk_mul_f32 v[8:9], v[8:9], v[0:1] op_sel_hi:[1,0]
	v_pk_mul_f32 v[6:7], v[6:7], v[0:1] op_sel_hi:[1,0]
	v_pk_mul_f32 v[4:5], v[4:5], v[0:1] op_sel_hi:[1,0]
	v_pk_mul_f32 v[2:3], v[2:3], v[0:1] op_sel_hi:[1,0]

.LBB0_352:
	s_mul_i32 s0, s5, 0xa000
	v_add_u32_e32 v185, s0, v176
	v_add_u32_e32 v187, s0, v178
	v_add_u32_e32 v192, s0, v180
	v_add_u32_e32 v193, s0, v182
	ds_read_b128 v[196:199], v185
	ds_read_b128 v[200:203], v187
	ds_read_b128 v[232:235], v185 offset:12288
	ds_read_b128 v[236:239], v187 offset:12288
	ds_read_b128 v[240:243], v192
	s_waitcnt lgkmcnt(4)
	v_mfma_f32_32x32x16_bf16 v[66:81], v[196:199], v[98:101], 0
	ds_read_b128 v[244:247], v192 offset:12288
	s_waitcnt lgkmcnt(4)
	v_mfma_f32_32x32x16_bf16 v[66:81], v[200:203], v[102:105], v[66:81]
	ds_read_b128 v[196:199], v193
	s_waitcnt lgkmcnt(4)
	v_mfma_f32_32x32x16_bf16 v[82:97], v[232:235], v[98:101], 0
	ds_read_b128 v[200:203], v193 offset:12288
	s_waitcnt lgkmcnt(4)
	v_mfma_f32_32x32x16_bf16 v[82:97], v[236:239], v[102:105], v[82:97]
	ds_read_b128 v[232:235], v185 offset:128
	s_waitcnt lgkmcnt(4)
	v_mfma_f32_32x32x16_bf16 v[66:81], v[240:243], v[106:109], v[66:81]
	ds_read_b128 v[236:239], v185 offset:12416
	s_waitcnt lgkmcnt(4)
	v_mfma_f32_32x32x16_bf16 v[82:97], v[244:247], v[106:109], v[82:97]
	ds_read_b128 v[240:243], v187 offset:128
	s_waitcnt lgkmcnt(4)
	v_mfma_f32_32x32x16_bf16 v[66:81], v[196:199], v[110:113], v[66:81]
	ds_read_b128 v[244:247], v187 offset:12416
	s_waitcnt lgkmcnt(4)
	v_mfma_f32_32x32x16_bf16 v[82:97], v[200:203], v[110:113], v[82:97]
	ds_read_b128 v[196:199], v192 offset:128
	s_waitcnt lgkmcnt(4)
	v_mfma_f32_32x32x16_bf16 v[66:81], v[232:235], v[114:117], v[66:81]
	ds_read_b128 v[200:203], v192 offset:12416
	s_waitcnt lgkmcnt(4)
	v_mfma_f32_32x32x16_bf16 v[82:97], v[236:239], v[114:117], v[82:97]
	ds_read_b128 v[232:235], v193 offset:128
	s_waitcnt lgkmcnt(4)
	v_mfma_f32_32x32x16_bf16 v[66:81], v[240:243], v[118:121], v[66:81]
	ds_read_b128 v[236:239], v193 offset:12416
	s_waitcnt lgkmcnt(4)
	v_mfma_f32_32x32x16_bf16 v[82:97], v[244:247], v[118:121], v[82:97]
	ds_read_b128 v[240:243], v185 offset:256
	s_waitcnt lgkmcnt(4)
	v_mfma_f32_32x32x16_bf16 v[66:81], v[196:199], v[122:125], v[66:81]
	ds_read_b128 v[244:247], v185 offset:12544
	s_waitcnt lgkmcnt(4)
	v_mfma_f32_32x32x16_bf16 v[82:97], v[200:203], v[122:125], v[82:97]
	ds_read_b128 v[196:199], v187 offset:256
	s_waitcnt lgkmcnt(4)
	v_mfma_f32_32x32x16_bf16 v[66:81], v[232:235], v[126:129], v[66:81]
	ds_read_b128 v[200:203], v187 offset:12544
	s_waitcnt lgkmcnt(4)
	v_mfma_f32_32x32x16_bf16 v[82:97], v[236:239], v[126:129], v[82:97]
	ds_read_b128 v[232:235], v192 offset:256
	s_waitcnt lgkmcnt(4)
	v_mfma_f32_32x32x16_bf16 v[66:81], v[240:243], v[130:133], v[66:81]
	ds_read_b128 v[236:239], v192 offset:12544
	s_waitcnt lgkmcnt(4)
	v_mfma_f32_32x32x16_bf16 v[82:97], v[244:247], v[130:133], v[82:97]
	ds_read_b128 v[240:243], v193 offset:12544
	s_waitcnt lgkmcnt(4)
	v_mfma_f32_32x32x16_bf16 v[66:81], v[196:199], v[134:137], v[66:81]
	ds_read_b128 v[244:247], v193 offset:256
	s_waitcnt lgkmcnt(4)
	v_mfma_f32_32x32x16_bf16 v[82:97], v[200:203], v[134:137], v[82:97]
	s_waitcnt lgkmcnt(3)
	v_mfma_f32_32x32x16_bf16 v[66:81], v[232:235], v[138:141], v[66:81]
	s_waitcnt lgkmcnt(2)
	v_mfma_f32_32x32x16_bf16 v[82:97], v[236:239], v[138:141], v[82:97]
	s_waitcnt lgkmcnt(1)
	v_mfma_f32_32x32x16_bf16 v[82:97], v[240:243], v[142:145], v[82:97]
	s_waitcnt lgkmcnt(0)
	v_mfma_f32_32x32x16_bf16 v[66:81], v[244:247], v[142:145], v[66:81]
	s_nop 1
	s_nop 8
	s_nop 7
	s_nop 4
	v_max3_f32 v185, v82, v83, v84
	v_max3_f32 v187, v66, v67, v68
	v_max3_f32 v185, v185, v85, v86
	v_max3_f32 v187, v187, v69, v70
	v_max3_f32 v185, v185, v87, v88
	v_max3_f32 v187, v187, v71, v72
	v_max3_f32 v185, v185, v89, v90
	v_max3_f32 v187, v187, v73, v74
	v_max3_f32 v185, v185, v91, v92
	v_max3_f32 v187, v187, v75, v76
	v_max3_f32 v185, v185, v93, v94
	v_max3_f32 v187, v187, v77, v78
	v_max3_f32 v185, v185, v95, v96
	v_max3_f32 v187, v187, v79, v80
	v_max3_f32 v187, v187, v81, v97
	v_max_f32_e32 v185, v185, v187
	v_and_b32_e32 v188, 64, v221
	v_xor_b32_e32 v187, 32, v221
	v_add_u32_e32 v188, 64, v188
	v_cmp_lt_i32_e32 vcc, v187, v188
	s_nop 1
	v_cndmask_b32_e32 v187, v221, v187, vcc
	v_lshlrev_b32_e32 v193, 2, v187
	ds_bpermute_b32 v187, v193, v185
	s_waitcnt lgkmcnt(0)
	v_max3_f32 v185, v186, v185, v187
	v_sub_f32_e32 v66, v66, v185
	v_exp_f32_e32 v187, v66
	v_sub_f32_e32 v66, v82, v185
	v_exp_f32_e32 v188, v66
	v_sub_f32_e32 v66, v67, v185
	v_exp_f32_e32 v67, v66
	v_sub_f32_e32 v66, v83, v185
	v_exp_f32_e32 v83, v66
	v_sub_f32_e32 v68, v68, v185
	v_sub_f32_e32 v84, v84, v185
	v_exp_f32_e32 v68, v68
	v_exp_f32_e32 v84, v84
	v_add_f32_e32 v82, v187, v188
	v_sub_f32_e32 v69, v69, v185
	v_sub_f32_e32 v85, v85, v185
	v_sub_f32_e32 v66, v186, v185
	v_add_f32_e32 v82, 0, v82
	v_add_f32_e32 v186, v67, v83
	v_exp_f32_e32 v69, v69
	v_exp_f32_e32 v85, v85
	v_add_f32_e32 v82, v186, v82
	v_add_f32_e32 v186, v68, v84
	v_sub_f32_e32 v70, v70, v185
	v_add_f32_e32 v82, v186, v82
	v_exp_f32_e32 v186, v70
	v_sub_f32_e32 v70, v86, v185
	v_exp_f32_e32 v86, v70
	v_sub_f32_e32 v70, v71, v185
	v_add_f32_e32 v190, v69, v85
	v_exp_f32_e32 v189, v70
	v_sub_f32_e32 v70, v87, v185
	v_sub_f32_e32 v72, v72, v185
	v_exp_f32_e32 v87, v70
	v_add_f32_e32 v70, v190, v82
	v_exp_f32_e32 v190, v72
	v_sub_f32_e32 v72, v88, v185
	v_exp_f32_e32 v88, v72
	v_add_f32_e32 v71, v186, v86
	v_add_f32_e32 v70, v71, v70
	v_add_f32_e32 v71, v189, v87
	v_sub_f32_e32 v72, v73, v185
	v_exp_f32_e32 v73, v72
	v_sub_f32_e32 v72, v89, v185
	v_add_f32_e32 v70, v71, v70
	v_add_f32_e32 v71, v190, v88
	v_exp_f32_e32 v89, v72
	v_add_f32_e32 v82, v71, v70
	v_sub_f32_e32 v70, v74, v185
	v_sub_f32_e32 v71, v90, v185
	v_exp_f32_e32 v70, v70
	v_exp_f32_e32 v71, v71
	v_sub_f32_e32 v72, v75, v185
	v_sub_f32_e32 v74, v91, v185
	v_exp_f32_e32 v72, v72
	v_exp_f32_e32 v75, v74
	v_sub_f32_e32 v76, v76, v185
	v_sub_f32_e32 v90, v92, v185
	v_sub_f32_e32 v78, v78, v185
	v_exp_f32_e32 v76, v76
	v_exp_f32_e32 v90, v90
	v_sub_f32_e32 v77, v77, v185
	v_sub_f32_e32 v91, v93, v185
	v_exp_f32_e32 v92, v78
	v_sub_f32_e32 v78, v94, v185
	v_add_f32_e32 v191, v73, v89
	v_exp_f32_e32 v77, v77
	v_exp_f32_e32 v91, v91
	v_exp_f32_e32 v93, v78
	v_sub_f32_e32 v78, v79, v185
	v_sub_f32_e32 v79, v80, v185
	v_add_f32_e32 v74, v191, v82
	v_add_f32_e32 v82, v70, v71
	v_exp_f32_e32 v94, v78
	v_sub_f32_e32 v78, v95, v185
	v_exp_f32_e32 v191, v79
	v_sub_f32_e32 v79, v96, v185
	v_add_f32_e32 v74, v82, v74
	v_add_f32_e32 v82, v72, v75
	v_exp_f32_e32 v95, v78
	v_exp_f32_e32 v96, v79
	v_sub_f32_e32 v79, v81, v185
	v_add_f32_e32 v74, v82, v74
	v_add_f32_e32 v82, v76, v90
	v_exp_f32_e32 v192, v79
	v_sub_f32_e32 v79, v97, v185
	v_add_f32_e32 v74, v82, v74
	v_add_f32_e32 v82, v77, v91
	v_exp_f32_e32 v97, v79
	v_add_f32_e32 v74, v82, v74
	v_add_f32_e32 v78, v92, v93
	v_add_f32_e32 v74, v78, v74
	v_add_f32_e32 v78, v94, v95
	v_add_f32_e32 v74, v78, v74
	v_add_f32_e32 v78, v191, v96
	v_add_f32_e32 v74, v78, v74
	v_add_f32_e32 v78, v192, v97
	v_add_f32_e32 v74, v78, v74
	v_exp_f32_e32 v66, v66
	ds_bpermute_b32 v78, v193, v74
	v_cmp_neq_f32_e32 vcc, 1.0, v66
	s_cbranch_vccz .LBB0_354
	v_pk_mul_f32 v[64:65], v[64:65], v[66:67] op_sel_hi:[1,0]
	v_pk_mul_f32 v[62:63], v[62:63], v[66:67] op_sel_hi:[1,0]
	v_pk_mul_f32 v[60:61], v[60:61], v[66:67] op_sel_hi:[1,0]
	v_pk_mul_f32 v[58:59], v[58:59], v[66:67] op_sel_hi:[1,0]
	v_pk_mul_f32 v[56:57], v[56:57], v[66:67] op_sel_hi:[1,0]
	v_pk_mul_f32 v[54:55], v[54:55], v[66:67] op_sel_hi:[1,0]
	v_pk_mul_f32 v[52:53], v[52:53], v[66:67] op_sel_hi:[1,0]
	v_pk_mul_f32 v[50:51], v[50:51], v[66:67] op_sel_hi:[1,0]
	v_pk_mul_f32 v[48:49], v[48:49], v[66:67] op_sel_hi:[1,0]
	v_pk_mul_f32 v[46:47], v[46:47], v[66:67] op_sel_hi:[1,0]
	v_pk_mul_f32 v[44:45], v[44:45], v[66:67] op_sel_hi:[1,0]
	v_pk_mul_f32 v[42:43], v[42:43], v[66:67] op_sel_hi:[1,0]
	v_pk_mul_f32 v[40:41], v[40:41], v[66:67] op_sel_hi:[1,0]
	v_pk_mul_f32 v[38:39], v[38:39], v[66:67] op_sel_hi:[1,0]
	v_pk_mul_f32 v[36:37], v[36:37], v[66:67] op_sel_hi:[1,0]
	v_pk_mul_f32 v[34:35], v[34:35], v[66:67] op_sel_hi:[1,0]
	v_pk_mul_f32 v[32:33], v[32:33], v[66:67] op_sel_hi:[1,0]
	v_pk_mul_f32 v[30:31], v[30:31], v[66:67] op_sel_hi:[1,0]
	v_pk_mul_f32 v[28:29], v[28:29], v[66:67] op_sel_hi:[1,0]
	v_pk_mul_f32 v[26:27], v[26:27], v[66:67] op_sel_hi:[1,0]
	v_pk_mul_f32 v[24:25], v[24:25], v[66:67] op_sel_hi:[1,0]
	v_pk_mul_f32 v[22:23], v[22:23], v[66:67] op_sel_hi:[1,0]
	v_pk_mul_f32 v[20:21], v[20:21], v[66:67] op_sel_hi:[1,0]
	v_pk_mul_f32 v[18:19], v[18:19], v[66:67] op_sel_hi:[1,0]
	v_pk_mul_f32 v[16:17], v[16:17], v[66:67] op_sel_hi:[1,0]
	v_pk_mul_f32 v[14:15], v[14:15], v[66:67] op_sel_hi:[1,0]
	v_pk_mul_f32 v[12:13], v[12:13], v[66:67] op_sel_hi:[1,0]
	v_pk_mul_f32 v[10:11], v[10:11], v[66:67] op_sel_hi:[1,0]
	v_pk_mul_f32 v[8:9], v[8:9], v[66:67] op_sel_hi:[1,0]
	v_pk_mul_f32 v[6:7], v[6:7], v[66:67] op_sel_hi:[1,0]
	v_pk_mul_f32 v[4:5], v[4:5], v[66:67] op_sel_hi:[1,0]
	v_pk_mul_f32 v[2:3], v[2:3], v[66:67] op_sel_hi:[1,0]

.LBB0_369:
	v_add_u32_e32 v99, s4, v94
	v_add_u32_e32 v98, s4, v93
	v_add_u32_e32 v97, s4, v92
	v_add_u32_e32 v95, s4, v91
	ds_read_b128 v[196:199], v99
	ds_read_b128 v[200:203], v98
	ds_read_b128 v[232:235], v99 offset:4096
	ds_read_b128 v[236:239], v98 offset:4096
	ds_read_b128 v[240:243], v97
	s_waitcnt lgkmcnt(4)
	v_mfma_f32_32x32x16_bf16 v[34:49], v[196:199], v[66:69], 0
	ds_read_b128 v[244:247], v97 offset:4096
	s_waitcnt lgkmcnt(4)
	v_mfma_f32_32x32x16_bf16 v[34:49], v[200:203], v[70:73], v[34:49]
	ds_read_b128 v[196:199], v95 offset:4096
	s_waitcnt lgkmcnt(4)
	v_mfma_f32_32x32x16_bf16 v[50:65], v[232:235], v[66:69], 0
	ds_read_b128 v[200:203], v95
	s_waitcnt lgkmcnt(4)
	v_mfma_f32_32x32x16_bf16 v[50:65], v[236:239], v[70:73], v[50:65]
	s_waitcnt lgkmcnt(3)
	v_mfma_f32_32x32x16_bf16 v[34:49], v[240:243], v[74:77], v[34:49]
	s_waitcnt lgkmcnt(2)
	v_mfma_f32_32x32x16_bf16 v[50:65], v[244:247], v[74:77], v[50:65]
	s_waitcnt lgkmcnt(1)
	v_mfma_f32_32x32x16_bf16 v[50:65], v[196:199], v[78:81], v[50:65]
	s_waitcnt lgkmcnt(0)
	v_mfma_f32_32x32x16_bf16 v[34:49], v[200:203], v[78:81], v[34:49]
	s_nop 1
	s_nop 8
	s_nop 7
	s_nop 4
	v_max3_f32 v0, v50, v51, v52
	v_max3_f32 v96, v34, v35, v36
	v_max3_f32 v0, v0, v53, v54
	v_max3_f32 v96, v96, v37, v38
	v_max3_f32 v0, v0, v55, v56
	v_max3_f32 v96, v96, v39, v40
	v_max3_f32 v0, v0, v57, v58
	v_max3_f32 v96, v96, v41, v42
	v_max3_f32 v0, v0, v59, v60
	v_max3_f32 v96, v96, v43, v44
	v_max3_f32 v0, v0, v61, v62
	v_max3_f32 v96, v96, v45, v46
	v_max3_f32 v0, v0, v63, v64
	v_max3_f32 v96, v96, v47, v48
	v_max3_f32 v96, v96, v49, v65
	v_max_f32_e32 v0, v0, v96
	v_and_b32_e32 v102, 64, v221
	v_xor_b32_e32 v96, 32, v221
	v_add_u32_e32 v102, 64, v102
	v_cmp_lt_i32_e32 vcc, v96, v102
	s_nop 1
	v_cndmask_b32_e32 v96, v221, v96, vcc
	v_lshlrev_b32_e32 v102, 2, v96
	ds_bpermute_b32 v96, v102, v0
	s_waitcnt lgkmcnt(0)
	v_max3_f32 v96, v101, v0, v96
	v_sub_f32_e32 v0, v34, v96
	v_exp_f32_e32 v34, v0
	v_sub_f32_e32 v0, v50, v96
	v_exp_f32_e32 v50, v0
	v_sub_f32_e32 v0, v35, v96
	v_exp_f32_e32 v35, v0
	v_sub_f32_e32 v0, v51, v96
	v_exp_f32_e32 v51, v0
	v_sub_f32_e32 v36, v36, v96
	v_sub_f32_e32 v52, v52, v96
	v_exp_f32_e32 v36, v36
	v_exp_f32_e32 v52, v52
	v_sub_f32_e32 v0, v101, v96
	v_add_f32_e32 v101, v34, v50
	v_add_f32_e32 v101, 0, v101
	v_add_f32_e32 v103, v35, v51
	v_add_f32_e32 v101, v103, v101
	v_add_f32_e32 v103, v36, v52
	v_sub_f32_e32 v38, v38, v96
	v_sub_f32_e32 v37, v37, v96
	v_sub_f32_e32 v53, v53, v96
	v_add_f32_e32 v103, v103, v101
	v_exp_f32_e32 v101, v38
	v_sub_f32_e32 v38, v54, v96
	v_exp_f32_e32 v37, v37
	v_exp_f32_e32 v53, v53
	v_exp_f32_e32 v54, v38
	v_sub_f32_e32 v38, v39, v96
	v_exp_f32_e32 v39, v38
	v_sub_f32_e32 v38, v55, v96
	v_exp_f32_e32 v55, v38
	v_sub_f32_e32 v40, v40, v96
	v_sub_f32_e32 v56, v56, v96
	v_exp_f32_e32 v40, v40
	v_exp_f32_e32 v56, v56
	v_sub_f32_e32 v41, v41, v96
	v_sub_f32_e32 v57, v57, v96
	v_add_f32_e32 v104, v37, v53
	v_exp_f32_e32 v41, v41
	v_exp_f32_e32 v57, v57
	v_sub_f32_e32 v42, v42, v96
	v_sub_f32_e32 v58, v58, v96
	v_add_f32_e32 v38, v104, v103
	v_add_f32_e32 v103, v101, v54
	v_exp_f32_e32 v42, v42
	v_exp_f32_e32 v58, v58
	v_sub_f32_e32 v43, v43, v96
	v_sub_f32_e32 v59, v59, v96
	v_add_f32_e32 v38, v103, v38
	v_add_f32_e32 v103, v39, v55
	v_exp_f32_e32 v43, v43
	v_exp_f32_e32 v59, v59
	v_sub_f32_e32 v44, v44, v96
	v_sub_f32_e32 v60, v60, v96
	v_add_f32_e32 v38, v103, v38
	v_add_f32_e32 v103, v40, v56
	v_exp_f32_e32 v44, v44
	v_exp_f32_e32 v60, v60
	v_sub_f32_e32 v45, v45, v96
	v_sub_f32_e32 v61, v61, v96
	v_add_f32_e32 v38, v103, v38
	v_add_f32_e32 v103, v41, v57
	v_exp_f32_e32 v45, v45
	v_exp_f32_e32 v61, v61
	v_sub_f32_e32 v46, v46, v96
	v_sub_f32_e32 v62, v62, v96
	v_add_f32_e32 v38, v103, v38
	v_add_f32_e32 v103, v42, v58
	v_exp_f32_e32 v46, v46
	v_exp_f32_e32 v62, v62
	v_sub_f32_e32 v47, v47, v96
	v_sub_f32_e32 v63, v63, v96
	v_add_f32_e32 v38, v103, v38
	v_add_f32_e32 v103, v43, v59
	v_exp_f32_e32 v47, v47
	v_exp_f32_e32 v63, v63
	v_sub_f32_e32 v48, v48, v96
	v_sub_f32_e32 v64, v64, v96
	v_add_f32_e32 v38, v103, v38
	v_add_f32_e32 v103, v44, v60
	v_exp_f32_e32 v48, v48
	v_exp_f32_e32 v64, v64
	v_sub_f32_e32 v49, v49, v96
	v_sub_f32_e32 v65, v65, v96
	v_add_f32_e32 v38, v103, v38
	v_add_f32_e32 v103, v45, v61
	v_exp_f32_e32 v49, v49
	v_exp_f32_e32 v65, v65
	v_add_f32_e32 v38, v103, v38
	v_add_f32_e32 v103, v46, v62
	v_add_f32_e32 v38, v103, v38
	v_add_f32_e32 v103, v47, v63
	v_add_f32_e32 v38, v103, v38
	v_add_f32_e32 v103, v48, v64
	v_add_f32_e32 v38, v103, v38
	v_add_f32_e32 v103, v49, v65
	v_add_f32_e32 v38, v103, v38
	v_exp_f32_e32 v0, v0
	ds_bpermute_b32 v102, v102, v38
	v_cmp_neq_f32_e32 vcc, 1.0, v0
	s_cbranch_vccz .LBB0_371
	v_pk_mul_f32 v[32:33], v[32:33], v[0:1] op_sel_hi:[1,0]
	v_pk_mul_f32 v[30:31], v[30:31], v[0:1] op_sel_hi:[1,0]
	v_pk_mul_f32 v[28:29], v[28:29], v[0:1] op_sel_hi:[1,0]
	v_pk_mul_f32 v[26:27], v[26:27], v[0:1] op_sel_hi:[1,0]
	v_pk_mul_f32 v[24:25], v[24:25], v[0:1] op_sel_hi:[1,0]
	v_pk_mul_f32 v[22:23], v[22:23], v[0:1] op_sel_hi:[1,0]
	v_pk_mul_f32 v[20:21], v[20:21], v[0:1] op_sel_hi:[1,0]
	v_pk_mul_f32 v[18:19], v[18:19], v[0:1] op_sel_hi:[1,0]
	v_pk_mul_f32 v[16:17], v[16:17], v[0:1] op_sel_hi:[1,0]
	v_pk_mul_f32 v[14:15], v[14:15], v[0:1] op_sel_hi:[1,0]
	v_pk_mul_f32 v[12:13], v[12:13], v[0:1] op_sel_hi:[1,0]
	v_pk_mul_f32 v[10:11], v[10:11], v[0:1] op_sel_hi:[1,0]
	v_pk_mul_f32 v[8:9], v[8:9], v[0:1] op_sel_hi:[1,0]
	v_pk_mul_f32 v[6:7], v[6:7], v[0:1] op_sel_hi:[1,0]
	v_pk_mul_f32 v[4:5], v[4:5], v[0:1] op_sel_hi:[1,0]
	v_pk_mul_f32 v[2:3], v[2:3], v[0:1] op_sel_hi:[1,0]

.LBB0_400:
	s_andn2_b64 vcc, exec, s[4:5]
	s_cbranch_vccnz .LBB0_408
	s_and_b32 s8, s17, 0xc000
	v_or_b32_e32 v50, s8, v94
	v_or_b32_e32 v204, s8, v95
	v_or_b32_e32 v205, s8, v96
	v_or_b32_e32 v248, s8, v97
	ds_read_b128 v[196:199], v50
	ds_read_b128 v[200:203], v204
	ds_read_b128 v[232:235], v50 offset:4096
	ds_read_b128 v[236:239], v204 offset:4096
	ds_read_b128 v[240:243], v205
	s_andn2_b64 vcc, exec, s[0:1]
	s_waitcnt lgkmcnt(4)
	v_mfma_f32_32x32x16_bf16 v[34:49], v[196:199], v[66:69], 0
	ds_read_b128 v[244:247], v205 offset:4096
	s_waitcnt lgkmcnt(4)
	v_mfma_f32_32x32x16_bf16 v[34:49], v[200:203], v[70:73], v[34:49]
	ds_read_b128 v[196:199], v248
	s_waitcnt lgkmcnt(4)
	v_mfma_f32_32x32x16_bf16 v[50:65], v[232:235], v[66:69], 0
	ds_read_b128 v[200:203], v248 offset:4096
	s_waitcnt lgkmcnt(4)
	v_mfma_f32_32x32x16_bf16 v[50:65], v[236:239], v[70:73], v[50:65]
	s_waitcnt lgkmcnt(3)
	v_mfma_f32_32x32x16_bf16 v[34:49], v[240:243], v[74:77], v[34:49]
	s_waitcnt lgkmcnt(2)
	v_mfma_f32_32x32x16_bf16 v[50:65], v[244:247], v[74:77], v[50:65]
	s_waitcnt lgkmcnt(1)
	v_mfma_f32_32x32x16_bf16 v[34:49], v[196:199], v[78:81], v[34:49]
	s_waitcnt lgkmcnt(0)
	v_mfma_f32_32x32x16_bf16 v[50:65], v[200:203], v[78:81], v[50:65]
	s_nop 1
	s_cbranch_vccnz .LBB0_405
	s_lshl_b32 s0, s54, 6
	s_sub_i32 s1, s9, s10
	s_add_i32 s0, s1, s0
	s_addk_i32 s0, 0xf000
	v_sub_u32_e32 v101, s0, v91
	v_add_u32_e32 v101, 63, v101
	v_subrev_u32_e32 v102, s0, v98
	v_max_i32_e32 v101, v101, v102
	s_movk_i32 s1, 0x80
	v_cmp_lt_i32_e32 vcc, s1, v101
	s_and_saveexec_b64 s[4:5], vcc
	s_cbranch_execz .LBB0_404
	v_add_u32_e32 v101, s0, v99
	s_movk_i32 s0, 0x101
	v_cmp_gt_u32_e32 vcc, s0, v101
	v_add_u32_e32 v102, 0xffffff1f, v101
	s_movk_i32 s0, 0xfefe
	v_cndmask_b32_e32 v34, v215, v34, vcc
	v_cmp_lt_u32_e32 vcc, s0, v102
	v_add_u32_e32 v102, 0xffffff00, v101
	s_nop 0
	v_cndmask_b32_e32 v50, v215, v50, vcc
	v_cmp_lt_u32_e32 vcc, s0, v102
	v_add_u32_e32 v102, 0xffffff20, v101
	s_nop 0
	v_cndmask_b32_e32 v35, v215, v35, vcc
	v_cmp_lt_u32_e32 vcc, s0, v102
	v_add_u32_e32 v102, 0xffffff01, v101
	s_nop 0
	v_cndmask_b32_e32 v51, v215, v51, vcc
	v_cmp_lt_u32_e32 vcc, s0, v102
	v_add_u32_e32 v102, 0xffffff21, v101
	s_nop 0
	v_cndmask_b32_e32 v36, v215, v36, vcc
	v_cmp_lt_u32_e32 vcc, s0, v102
	v_add_u32_e32 v102, 0xffffff02, v101
	s_nop 0
	v_cndmask_b32_e32 v52, v215, v52, vcc
	v_cmp_lt_u32_e32 vcc, s0, v102
	v_add_u32_e32 v102, 0xffffff22, v101
	s_nop 0
	v_cndmask_b32_e32 v37, v215, v37, vcc
	v_cmp_lt_u32_e32 vcc, s0, v102
	v_add_u32_e32 v102, 0xffffff07, v101
	s_nop 0
	v_cndmask_b32_e32 v53, v215, v53, vcc
	v_cmp_lt_u32_e32 vcc, s0, v102
	v_add_u32_e32 v102, 0xffffff27, v101
	s_nop 0
	v_cndmask_b32_e32 v38, v215, v38, vcc
	v_cmp_lt_u32_e32 vcc, s0, v102
	v_add_u32_e32 v102, 0xffffff08, v101
	s_nop 0
	v_cndmask_b32_e32 v54, v215, v54, vcc
	v_cmp_lt_u32_e32 vcc, s0, v102
	v_add_u32_e32 v102, 0xffffff28, v101
	s_nop 0
	v_cndmask_b32_e32 v39, v215, v39, vcc
	v_cmp_lt_u32_e32 vcc, s0, v102
	v_add_u32_e32 v102, 0xffffff09, v101
	s_nop 0
	v_cndmask_b32_e32 v55, v215, v55, vcc
	v_cmp_lt_u32_e32 vcc, s0, v102
	v_add_u32_e32 v102, 0xffffff29, v101
	s_nop 0
	v_cndmask_b32_e32 v40, v215, v40, vcc
	v_cmp_lt_u32_e32 vcc, s0, v102
	v_add_u32_e32 v102, 0xffffff0a, v101
	s_nop 0
	v_cndmask_b32_e32 v56, v215, v56, vcc
	v_cmp_lt_u32_e32 vcc, s0, v102
	v_add_u32_e32 v102, 0xffffff2a, v101
	s_nop 0
	v_cndmask_b32_e32 v41, v215, v41, vcc
	v_cmp_lt_u32_e32 vcc, s0, v102
	v_add_u32_e32 v102, 0xffffff0f, v101
	s_nop 0
	v_cndmask_b32_e32 v57, v215, v57, vcc
	v_cmp_lt_u32_e32 vcc, s0, v102
	v_add_u32_e32 v102, 0xffffff2f, v101
	s_nop 0
	v_cndmask_b32_e32 v42, v215, v42, vcc
	v_cmp_lt_u32_e32 vcc, s0, v102
	v_add_u32_e32 v102, 0xffffff10, v101
	s_nop 0
	v_cndmask_b32_e32 v58, v215, v58, vcc
	v_cmp_lt_u32_e32 vcc, s0, v102
	v_add_u32_e32 v102, 0xffffff30, v101
	s_nop 0
	v_cndmask_b32_e32 v43, v215, v43, vcc
	v_cmp_lt_u32_e32 vcc, s0, v102
	v_add_u32_e32 v102, 0xffffff11, v101
	s_nop 0
	v_cndmask_b32_e32 v59, v215, v59, vcc
	v_cmp_lt_u32_e32 vcc, s0, v102
	v_add_u32_e32 v102, 0xffffff31, v101
	s_nop 0
	v_cndmask_b32_e32 v44, v215, v44, vcc
	v_cmp_lt_u32_e32 vcc, s0, v102
	v_add_u32_e32 v102, 0xffffff12, v101
	s_nop 0
	v_cndmask_b32_e32 v60, v215, v60, vcc
	v_cmp_lt_u32_e32 vcc, s0, v102
	v_add_u32_e32 v102, 0xffffff32, v101
	s_nop 0
	v_cndmask_b32_e32 v45, v215, v45, vcc
	v_cmp_lt_u32_e32 vcc, s0, v102
	v_add_u32_e32 v102, 0xffffff17, v101
	s_nop 0
	v_cndmask_b32_e32 v61, v215, v61, vcc
	v_cmp_lt_u32_e32 vcc, s0, v102
	v_add_u32_e32 v102, 0xffffff37, v101
	s_nop 0
	v_cndmask_b32_e32 v46, v215, v46, vcc
	v_cmp_lt_u32_e32 vcc, s0, v102
	v_add_u32_e32 v102, 0xffffff18, v101
	s_nop 0
	v_cndmask_b32_e32 v62, v215, v62, vcc
	v_cmp_lt_u32_e32 vcc, s0, v102
	v_add_u32_e32 v102, 0xffffff38, v101
	s_nop 0
	v_cndmask_b32_e32 v47, v215, v47, vcc
	v_cmp_lt_u32_e32 vcc, s0, v102
	v_add_u32_e32 v102, 0xffffff19, v101
	s_nop 0
	v_cndmask_b32_e32 v63, v215, v63, vcc
	v_cmp_lt_u32_e32 vcc, s0, v102
	v_add_u32_e32 v102, 0xffffff39, v101
	s_nop 0
	v_cndmask_b32_e32 v48, v215, v48, vcc
	v_cmp_lt_u32_e32 vcc, s0, v102
	v_add_u32_e32 v102, 0xffffff1a, v101
	v_add_u32_e32 v101, 0xffffff3a, v101
	v_cndmask_b32_e32 v64, v215, v64, vcc
	v_cmp_lt_u32_e32 vcc, s0, v102
	s_nop 1
	v_cndmask_b32_e32 v49, v215, v49, vcc
	v_cmp_lt_u32_e32 vcc, s0, v101
	s_nop 1
	v_cndmask_b32_e32 v65, v215, v65, vcc
.LBB0_404:
	s_or_b64 exec, exec, s[4:5]
.LBB0_405:
	s_nop 7
	s_nop 4
	v_max3_f32 v101, v50, v51, v52
	v_max3_f32 v102, v34, v35, v36
	v_max3_f32 v101, v101, v53, v54
	v_max3_f32 v102, v102, v37, v38
	v_max3_f32 v101, v101, v55, v56
	v_max3_f32 v102, v102, v39, v40
	v_max3_f32 v101, v101, v57, v58
	v_max3_f32 v102, v102, v41, v42
	v_max3_f32 v101, v101, v59, v60
	v_max3_f32 v102, v102, v43, v44
	v_max3_f32 v101, v101, v61, v62
	v_max3_f32 v102, v102, v45, v46
	v_max3_f32 v101, v101, v63, v64
	v_max3_f32 v102, v102, v47, v48
	v_max3_f32 v102, v102, v49, v65
	v_max_f32_e32 v101, v101, v102
	v_and_b32_e32 v103, 64, v221
	v_xor_b32_e32 v102, 32, v221
	v_add_u32_e32 v103, 64, v103
	v_cmp_lt_i32_e32 vcc, v102, v103
	s_mov_b32 s54, s2
	s_nop 0
	v_cndmask_b32_e32 v102, v221, v102, vcc
	v_lshlrev_b32_e32 v105, 2, v102
	ds_bpermute_b32 v102, v105, v101
	s_waitcnt lgkmcnt(0)
	v_max3_f32 v101, v0, v101, v102
	v_sub_f32_e32 v34, v34, v101
	v_sub_f32_e32 v50, v50, v101
	v_exp_f32_e32 v34, v34
	v_exp_f32_e32 v50, v50
	v_sub_f32_e32 v35, v35, v101
	v_sub_f32_e32 v51, v51, v101
	v_exp_f32_e32 v35, v35
	v_exp_f32_e32 v51, v51
	v_sub_f32_e32 v36, v36, v101
	v_sub_f32_e32 v52, v52, v101
	v_exp_f32_e32 v36, v36
	v_exp_f32_e32 v52, v52
	v_add_f32_e32 v102, v34, v50
	v_sub_f32_e32 v37, v37, v101
	v_sub_f32_e32 v53, v53, v101
	v_add_f32_e32 v102, 0, v102
	v_add_f32_e32 v103, v35, v51
	v_exp_f32_e32 v37, v37
	v_exp_f32_e32 v53, v53
	v_add_f32_e32 v102, v103, v102
	v_add_f32_e32 v103, v36, v52
	v_sub_f32_e32 v38, v38, v101
	v_add_f32_e32 v104, v103, v102
	v_exp_f32_e32 v102, v38
	v_sub_f32_e32 v38, v54, v101
	v_exp_f32_e32 v54, v38
	v_sub_f32_e32 v38, v39, v101
	v_add_f32_e32 v106, v37, v53
	v_exp_f32_e32 v103, v38
	v_sub_f32_e32 v38, v55, v101
	v_sub_f32_e32 v40, v40, v101
	v_exp_f32_e32 v55, v38
	v_add_f32_e32 v38, v106, v104
	v_exp_f32_e32 v104, v40
	v_sub_f32_e32 v40, v56, v101
	v_exp_f32_e32 v56, v40
	v_add_f32_e32 v39, v102, v54
	v_add_f32_e32 v38, v39, v38
	v_add_f32_e32 v39, v103, v55
	v_sub_f32_e32 v40, v41, v101
	v_exp_f32_e32 v41, v40
	v_sub_f32_e32 v40, v57, v101
	v_add_f32_e32 v38, v39, v38
	v_add_f32_e32 v39, v104, v56
	v_exp_f32_e32 v57, v40
	v_add_f32_e32 v106, v39, v38
	v_sub_f32_e32 v38, v42, v101
	v_sub_f32_e32 v39, v58, v101
	v_exp_f32_e32 v38, v38
	v_exp_f32_e32 v39, v39
	v_add_f32_e32 v107, v41, v57
	v_sub_f32_e32 v40, v43, v101
	v_sub_f32_e32 v42, v59, v101
	v_add_f32_e32 v43, v107, v106
	v_add_f32_e32 v58, v38, v39
	v_exp_f32_e32 v40, v40
	v_exp_f32_e32 v42, v42
	v_add_f32_e32 v59, v58, v43
	v_sub_f32_e32 v43, v44, v101
	v_sub_f32_e32 v44, v60, v101
	v_exp_f32_e32 v43, v43
	v_exp_f32_e32 v44, v44
	v_add_f32_e32 v106, v40, v42
	v_sub_f32_e32 v45, v45, v101
	v_sub_f32_e32 v58, v61, v101
	v_add_f32_e32 v59, v106, v59
	v_add_f32_e32 v60, v43, v44
	v_exp_f32_e32 v45, v45
	v_exp_f32_e32 v58, v58
	v_add_f32_e32 v61, v60, v59
	v_sub_f32_e32 v46, v46, v101
	v_sub_f32_e32 v59, v62, v101
	v_exp_f32_e32 v46, v46
	v_exp_f32_e32 v59, v59
	v_add_f32_e32 v106, v45, v58
	v_sub_f32_e32 v47, v47, v101
	v_sub_f32_e32 v60, v63, v101
	v_add_f32_e32 v61, v106, v61
	v_add_f32_e32 v62, v46, v59
	v_exp_f32_e32 v47, v47
	v_exp_f32_e32 v60, v60
	v_add_f32_e32 v63, v62, v61
	v_sub_f32_e32 v48, v48, v101
	v_sub_f32_e32 v61, v64, v101
	v_exp_f32_e32 v48, v48
	v_exp_f32_e32 v61, v61
	v_sub_f32_e32 v49, v49, v101
	v_sub_f32_e32 v62, v65, v101
	v_exp_f32_e32 v49, v49
	v_exp_f32_e32 v62, v62
	v_add_f32_e32 v106, v47, v60
	v_add_f32_e32 v63, v106, v63
	v_add_f32_e32 v64, v48, v61
	v_add_f32_e32 v63, v64, v63
	v_add_f32_e32 v64, v49, v62
	v_sub_f32_e32 v0, v0, v101
	v_add_f32_e32 v63, v64, v63
	v_exp_f32_e32 v0, v0
	ds_bpermute_b32 v64, v105, v63
	v_cmp_neq_f32_e32 vcc, 1.0, v0
	s_cbranch_vccz .LBB0_407
	v_pk_mul_f32 v[16:17], v[16:17], v[0:1] op_sel_hi:[1,0]
	v_pk_mul_f32 v[14:15], v[14:15], v[0:1] op_sel_hi:[1,0]
	v_pk_mul_f32 v[12:13], v[12:13], v[0:1] op_sel_hi:[1,0]
	v_pk_mul_f32 v[10:11], v[10:11], v[0:1] op_sel_hi:[1,0]
	v_pk_mul_f32 v[8:9], v[8:9], v[0:1] op_sel_hi:[1,0]
	v_pk_mul_f32 v[6:7], v[6:7], v[0:1] op_sel_hi:[1,0]
	v_pk_mul_f32 v[4:5], v[4:5], v[0:1] op_sel_hi:[1,0]
	v_pk_mul_f32 v[2:3], v[2:3], v[0:1] op_sel_hi:[1,0]
	v_pk_mul_f32 v[32:33], v[32:33], v[0:1] op_sel_hi:[1,0]
	v_pk_mul_f32 v[30:31], v[30:31], v[0:1] op_sel_hi:[1,0]
	v_pk_mul_f32 v[28:29], v[28:29], v[0:1] op_sel_hi:[1,0]
	v_pk_mul_f32 v[26:27], v[26:27], v[0:1] op_sel_hi:[1,0]
	v_pk_mul_f32 v[24:25], v[24:25], v[0:1] op_sel_hi:[1,0]
	v_pk_mul_f32 v[22:23], v[22:23], v[0:1] op_sel_hi:[1,0]
	v_pk_mul_f32 v[20:21], v[20:21], v[0:1] op_sel_hi:[1,0]
	v_pk_mul_f32 v[18:19], v[18:19], v[0:1] op_sel_hi:[1,0]
.LBB0_407:
	v_add_u32_e32 v204, s8, v94
	v_add_u32_e32 v205, s8, v95
	v_add_u32_e32 v248, s8, v96
	v_add_u32_e32 v249, s8, v97
	ds_read_b128 v[196:199], v204 offset:8192
	ds_read_b128 v[200:203], v205 offset:8192
	ds_read_b128 v[232:235], v248 offset:8192
	ds_read_b128 v[236:239], v249 offset:8192
	ds_read_b128 v[240:243], v204 offset:12288
	s_waitcnt lgkmcnt(5)
	v_add_f32_e32 v63, v63, v64
	v_fmac_f32_e32 v63, v100, v0
	v_cvt_pk_bf16_f32 v106, v34, v35
	v_cvt_pk_bf16_f32 v34, v39, v42
	v_cvt_pk_bf16_f32 v111, v43, v45
	v_cvt_pk_bf16_f32 v35, v44, v58
	v_cvt_pk_bf16_f32 v107, v36, v37
	v_cvt_pk_bf16_f32 v108, v102, v103
	v_cvt_pk_bf16_f32 v112, v46, v47
	v_cvt_pk_bf16_f32 v109, v104, v41
	v_cvt_pk_bf16_f32 v110, v38, v40
	s_waitcnt lgkmcnt(4)
	v_mfma_f32_32x32x16_bf16 v[18:33], v[196:199], v[106:109], v[18:33]
	ds_read_b128 v[244:247], v205 offset:12288
	v_cvt_pk_bf16_f32 v113, v48, v49
	v_cvt_pk_bf16_f32 v38, v50, v51
	v_cvt_pk_bf16_f32 v39, v52, v53
	v_cvt_pk_bf16_f32 v40, v54, v55
	v_cvt_pk_bf16_f32 v41, v56, v57
	s_waitcnt lgkmcnt(4)
	v_mfma_f32_32x32x16_bf16 v[18:33], v[200:203], v[110:113], v[18:33]
	ds_read_b128 v[196:199], v248 offset:12288
	v_cvt_pk_bf16_f32 v36, v59, v60
	v_cvt_pk_bf16_f32 v37, v61, v62
	v_mov_b32_e32 v100, v63
	s_waitcnt lgkmcnt(4)
	v_mfma_f32_32x32x16_bf16 v[18:33], v[232:235], v[38:41], v[18:33]
	ds_read_b128 v[200:203], v249 offset:12288
	s_waitcnt lgkmcnt(4)
	v_mfma_f32_32x32x16_bf16 v[18:33], v[236:239], v[34:37], v[18:33]
	s_waitcnt lgkmcnt(3)
	v_mfma_f32_32x32x16_bf16 v[2:17], v[240:243], v[106:109], v[2:17]
	s_waitcnt lgkmcnt(2)
	v_mfma_f32_32x32x16_bf16 v[2:17], v[244:247], v[110:113], v[2:17]
	s_waitcnt lgkmcnt(1)
	v_mfma_f32_32x32x16_bf16 v[2:17], v[196:199], v[38:41], v[2:17]
	s_waitcnt lgkmcnt(0)
	v_mfma_f32_32x32x16_bf16 v[2:17], v[200:203], v[34:37], v[2:17]
	s_branch .LBB0_409

.LBB0_421:
	v_mov_b32_e32 v17, 0
	s_cmp_lt_i32 s52, -15
	v_lshlrev_b32_e32 v106, 2, v37
	v_mov_b32_e32 v16, v17
	v_mov_b32_e32 v15, v17
	v_mov_b32_e32 v14, v17
	v_mov_b32_e32 v13, v17
	v_mov_b32_e32 v12, v17
	v_mov_b32_e32 v11, v17
	v_mov_b32_e32 v10, v17
	v_mov_b32_e32 v9, v17
	v_mov_b32_e32 v8, v17
	v_mov_b32_e32 v7, v17
	v_mov_b32_e32 v6, v17
	v_mov_b32_e32 v5, v17
	v_mov_b32_e32 v4, v17
	v_mov_b32_e32 v3, v17
	v_mov_b32_e32 v2, v17
	v_mov_b32_e32 v33, v17
	v_mov_b32_e32 v32, v17
	v_mov_b32_e32 v31, v17
	v_mov_b32_e32 v30, v17
	v_mov_b32_e32 v29, v17
	v_mov_b32_e32 v28, v17
	v_mov_b32_e32 v27, v17
	v_mov_b32_e32 v26, v17
	v_mov_b32_e32 v25, v17
	v_mov_b32_e32 v24, v17
	v_mov_b32_e32 v23, v17
	v_mov_b32_e32 v22, v17
	v_mov_b32_e32 v21, v17
	v_mov_b32_e32 v20, v17
	v_mov_b32_e32 v19, v17
	v_mov_b32_e32 v18, v17
	v_mov_b32_e32 v115, v17
	s_cbranch_scc1 .LBB0_477
	v_lshl_add_u64 v[100:101], s[4:5], 0, v[0:1]
	v_max_i32_e32 v0, 4, v105
	v_add_u32_e32 v0, -4, v0
	v_min_u32_e32 v0, 24, v0
	v_sub_u32_e32 v108, v0, v36
	v_lshrrev_b32_e32 v0, 1, v38
	v_bfe_u32 v2, v38, 1, 3
	v_lshlrev_b32_e32 v3, 7, v104
	v_bitop3_b32 v0, v37, v0, 7 bitop3:0x78
	v_lshl_or_b32 v110, v0, 4, v3
	v_bitop3_b32 v0, v37, v2, 2 bitop3:0x36
	v_lshl_or_b32 v111, v0, 4, v3
	v_bitop3_b32 v0, v37, v2, 4 bitop3:0x36
	v_lshl_or_b32 v112, v0, 4, v3
	v_bitop3_b32 v0, v37, v2, 6 bitop3:0x36
	v_lshl_or_b32 v113, v0, 4, v3
	v_or_b32_e32 v0, v104, v170
	v_sub_u32_e64 v2, v0, 8 clamp
	v_min_u32_e32 v2, 48, v2
	v_or_b32_e32 v3, 32, v106
	v_sub_u32_e32 v3, v3, v2
	v_sub_u32_e32 v4, v106, v2
	v_cmp_gt_u32_e64 s[42:43], 16, v3
	v_or_b32_e32 v3, 1, v106
	v_cmp_gt_u32_e64 s[40:41], 16, v4
	v_or_b32_e32 v4, 33, v106
	v_sub_u32_e32 v3, v3, v2
	v_cmp_gt_u32_e64 s[44:45], 16, v3
	v_sub_u32_e32 v3, v4, v2
	v_cmp_gt_u32_e64 s[46:47], 16, v3
	v_or_b32_e32 v3, 2, v106
	v_or_b32_e32 v4, 34, v106
	v_sub_u32_e32 v3, v3, v2
	v_cmp_gt_u32_e64 s[48:49], 16, v3
	v_sub_u32_e32 v3, v4, v2
	v_cmp_gt_u32_e64 s[50:51], 16, v3
	v_or_b32_e32 v3, 3, v106
	v_sub_u32_e32 v3, v3, v2
	v_or_b32_e32 v4, 35, v106
	v_cmp_gt_u32_e64 s[0:1], 16, v3
	v_sub_u32_e32 v3, v4, v2
	v_or_b32_e32 v4, 40, v106
	v_writelane_b32 v254, s0, 59
	s_mov_b32 s38, s14
	v_lshlrev_b32_e32 v0, 2, v0
	v_writelane_b32 v254, s1, 60
	v_cmp_gt_u32_e64 s[0:1], 16, v3
	v_or_b32_e32 v3, 8, v106
	v_sub_u32_e32 v3, v3, v2
	v_writelane_b32 v254, s0, 61
	v_sub_u32_e32 v0, v165, v0
	v_mov_b32_e32 v115, 0
	v_writelane_b32 v254, s1, 62
	v_cmp_gt_u32_e64 s[0:1], 16, v3
	v_sub_u32_e32 v3, v4, v2
	v_or_b32_e32 v4, 41, v106
	v_writelane_b32 v254, s0, 63
	s_mov_b64 s[36:37], s[72:73]
	v_lshl_add_u64 v[102:103], s[8:9], 0, v[34:35]
	v_writelane_b32 v255, s1, 0
	v_cmp_gt_u32_e64 s[0:1], 16, v3
	v_or_b32_e32 v3, 9, v106
	v_sub_u32_e32 v3, v3, v2
	v_writelane_b32 v255, s0, 1
	v_add_u32_e32 v109, 8, v108
	s_add_i32 s66, s52, 16
	v_writelane_b32 v255, s1, 2
	v_cmp_gt_u32_e64 s[0:1], 16, v3
	v_sub_u32_e32 v3, v4, v2
	v_or_b32_e32 v4, 42, v106
	v_writelane_b32 v255, s0, 3
	s_add_i32 s96, s52, 14
	s_add_i32 s52, s52, 15
	v_writelane_b32 v255, s1, 4
	v_cmp_gt_u32_e64 s[0:1], 16, v3
	v_or_b32_e32 v3, 10, v106
	v_sub_u32_e32 v3, v3, v2
	v_writelane_b32 v255, s0, 5
	v_lshl_add_u32 v114, v106, 2, v0
	v_mov_b32_e32 v0, 0xf149f2ca
	v_writelane_b32 v255, s1, 6
	v_cmp_gt_u32_e64 s[0:1], 16, v3
	v_sub_u32_e32 v3, v4, v2
	v_or_b32_e32 v4, 43, v106
	v_writelane_b32 v255, s0, 7
	s_mov_b32 s56, 0
	s_movk_i32 s12, 0xc0
	v_writelane_b32 v255, s1, 8
	v_cmp_gt_u32_e64 s[0:1], 16, v3
	v_or_b32_e32 v3, 11, v106
	v_sub_u32_e32 v3, v3, v2
	v_writelane_b32 v255, s0, 9
	s_mov_b32 s13, 0
	v_mov_b32_e32 v18, 0
	v_writelane_b32 v255, s1, 10
	v_cmp_gt_u32_e64 s[0:1], 16, v3
	v_sub_u32_e32 v3, v4, v2
	v_or_b32_e32 v4, 48, v106
	v_writelane_b32 v255, s0, 11
	v_mov_b32_e32 v19, v115
	v_mov_b32_e32 v20, v115
	v_writelane_b32 v255, s1, 12
	v_cmp_gt_u32_e64 s[0:1], 16, v3
	v_or_b32_e32 v3, 16, v106
	v_sub_u32_e32 v3, v3, v2
	v_writelane_b32 v255, s0, 13
	v_mov_b32_e32 v21, v115
	v_mov_b32_e32 v22, v115
	v_writelane_b32 v255, s1, 14
	v_cmp_gt_u32_e64 s[0:1], 16, v3
	v_sub_u32_e32 v3, v4, v2
	v_or_b32_e32 v4, 49, v106
	v_writelane_b32 v255, s0, 15
	v_mov_b32_e32 v23, v115
	v_mov_b32_e32 v24, v115
	v_writelane_b32 v255, s1, 16
	v_cmp_gt_u32_e64 s[0:1], 16, v3
	v_or_b32_e32 v3, 17, v106
	v_sub_u32_e32 v3, v3, v2
	v_writelane_b32 v255, s0, 17
	v_mov_b32_e32 v25, v115
	v_mov_b32_e32 v26, v115
	v_writelane_b32 v255, s1, 18
	v_cmp_gt_u32_e64 s[0:1], 16, v3
	v_sub_u32_e32 v3, v4, v2
	v_or_b32_e32 v4, 50, v106
	v_writelane_b32 v255, s0, 19
	v_mov_b32_e32 v27, v115
	v_mov_b32_e32 v28, v115
	v_writelane_b32 v255, s1, 20
	v_cmp_gt_u32_e64 s[0:1], 16, v3
	v_or_b32_e32 v3, 18, v106
	v_sub_u32_e32 v3, v3, v2
	v_writelane_b32 v255, s0, 21
	v_mov_b32_e32 v29, v115
	v_mov_b32_e32 v30, v115
	v_writelane_b32 v255, s1, 22
	v_cmp_gt_u32_e64 s[0:1], 16, v3
	v_sub_u32_e32 v3, v4, v2
	v_or_b32_e32 v4, 51, v106
	v_writelane_b32 v255, s0, 23
	v_mov_b32_e32 v31, v115
	v_mov_b32_e32 v32, v115
	v_writelane_b32 v255, s1, 24
	v_cmp_gt_u32_e64 s[0:1], 16, v3
	v_or_b32_e32 v3, 19, v106
	v_sub_u32_e32 v3, v3, v2
	v_writelane_b32 v255, s0, 25
	v_mov_b32_e32 v33, v115
	v_mov_b32_e32 v5, v115
	v_writelane_b32 v255, s1, 26
	v_cmp_gt_u32_e64 s[0:1], 16, v3
	v_sub_u32_e32 v3, v4, v2
	v_or_b32_e32 v4, 56, v106
	v_writelane_b32 v255, s0, 27
	v_mov_b32_e32 v6, v115
	v_mov_b32_e32 v7, v115
	v_writelane_b32 v255, s1, 28
	v_cmp_gt_u32_e64 s[0:1], 16, v3
	v_or_b32_e32 v3, 24, v106
	v_sub_u32_e32 v3, v3, v2
	v_writelane_b32 v255, s0, 29
	v_mov_b32_e32 v8, v115
	v_mov_b32_e32 v9, v115
	v_writelane_b32 v255, s1, 30
	v_cmp_gt_u32_e64 s[0:1], 16, v3
	v_sub_u32_e32 v3, v4, v2
	v_or_b32_e32 v4, 57, v106
	v_writelane_b32 v255, s0, 31
	v_mov_b32_e32 v10, v115
	v_mov_b32_e32 v11, v115
	v_writelane_b32 v255, s1, 32
	v_cmp_gt_u32_e64 s[0:1], 16, v3
	v_or_b32_e32 v3, 25, v106
	v_sub_u32_e32 v3, v3, v2
	v_writelane_b32 v255, s0, 33
	v_mov_b32_e32 v12, v115
	v_mov_b32_e32 v13, v115
	v_writelane_b32 v255, s1, 34
	v_cmp_gt_u32_e64 s[0:1], 16, v3
	v_sub_u32_e32 v3, v4, v2
	v_or_b32_e32 v4, 58, v106
	v_writelane_b32 v255, s0, 35
	v_mov_b32_e32 v14, v115
	v_mov_b32_e32 v15, v115
	v_writelane_b32 v255, s1, 36
	v_cmp_gt_u32_e64 s[0:1], 16, v3
	v_or_b32_e32 v3, 26, v106
	v_sub_u32_e32 v3, v3, v2
	v_cmp_gt_u32_e64 s[14:15], 16, v3
	v_sub_u32_e32 v3, v4, v2
	v_cmp_gt_u32_e64 s[16:17], 16, v3
	v_or_b32_e32 v3, 27, v106
	v_or_b32_e32 v4, 59, v106
	v_writelane_b32 v255, s0, 37
	v_sub_u32_e32 v3, v3, v2
	v_sub_u32_e32 v2, v4, v2
	v_writelane_b32 v255, s1, 38
	v_cmp_gt_u32_e64 s[8:9], 16, v3
	v_cmp_gt_u32_e64 s[72:73], 16, v2
	v_mov_b32_e32 v2, v115
	v_mov_b32_e32 v3, v115
	v_mov_b32_e32 v4, v115
	v_mov_b32_e32 v16, v115
	v_mov_b32_e32 v17, v115
	s_waitcnt vmcnt(0)
	s_branch .LBB0_425
.LBB0_423:
	v_add_u32_e32 v204, s4, v110
	v_add_u32_e32 v205, s4, v111
	v_add_u32_e32 v248, s4, v112
	v_add_u32_e32 v249, s4, v113
	ds_read_b128 v[196:199], v204 offset:8192
	ds_read_b128 v[200:203], v205 offset:8192
	ds_read_b128 v[232:235], v248 offset:8192
	ds_read_b128 v[236:239], v249 offset:8192
	ds_read_b128 v[240:243], v204 offset:12288
	s_waitcnt lgkmcnt(5)
	v_add_f32_e32 v63, v63, v64
	v_fmac_f32_e32 v63, v115, v0
	v_cvt_pk_bf16_f32 v70, v38, v40
	v_cvt_pk_bf16_f32 v38, v34, v35
	v_cvt_pk_bf16_f32 v34, v39, v42
	v_cvt_pk_bf16_f32 v71, v43, v58
	v_cvt_pk_bf16_f32 v35, v44, v45
	v_cvt_pk_bf16_f32 v50, v50, v51
	v_cvt_pk_bf16_f32 v51, v52, v53
	v_cvt_pk_bf16_f32 v39, v36, v37
	v_cvt_pk_bf16_f32 v52, v54, v55
	v_cvt_pk_bf16_f32 v36, v46, v47
	v_cvt_pk_bf16_f32 v53, v56, v57
	v_cvt_pk_bf16_f32 v72, v59, v60
	s_waitcnt lgkmcnt(4)
	v_mfma_f32_32x32x16_bf16 v[18:33], v[196:199], v[50:53], v[18:33]
	ds_read_b128 v[244:247], v205 offset:12288
	v_cvt_pk_bf16_f32 v73, v61, v62
	v_cvt_pk_bf16_f32 v40, v67, v68
	v_cvt_pk_bf16_f32 v41, v69, v41
	v_cvt_pk_bf16_f32 v37, v48, v49
	s_waitcnt lgkmcnt(4)
	v_mfma_f32_32x32x16_bf16 v[18:33], v[200:203], v[70:73], v[18:33]
	ds_read_b128 v[196:199], v248 offset:12288
	v_mov_b32_e32 v115, v63
	s_waitcnt lgkmcnt(4)
	v_mfma_f32_32x32x16_bf16 v[18:33], v[232:235], v[38:41], v[18:33]
	ds_read_b128 v[200:203], v249 offset:12288
	s_waitcnt lgkmcnt(4)
	v_mfma_f32_32x32x16_bf16 v[18:33], v[236:239], v[34:37], v[18:33]
	v_mov_b32_e32 v0, v66
	s_waitcnt lgkmcnt(3)
	v_mfma_f32_32x32x16_bf16 v[2:17], v[240:243], v[50:53], v[2:17]
	s_waitcnt lgkmcnt(2)
	v_mfma_f32_32x32x16_bf16 v[2:17], v[244:247], v[70:73], v[2:17]
	s_waitcnt lgkmcnt(1)
	v_mfma_f32_32x32x16_bf16 v[2:17], v[196:199], v[38:41], v[2:17]
	s_waitcnt lgkmcnt(0)
	v_mfma_f32_32x32x16_bf16 v[2:17], v[200:203], v[34:37], v[2:17]

.LBB0_439:
	v_cmp_ge_i32_e32 vcc, s13, v108
	v_cmp_lt_i32_e64 s[76:77], s13, v109
	s_and_b64 s[4:5], vcc, s[76:77]
	s_andn2_b64 s[0:1], s[0:1], exec
	s_and_b64 s[4:5], s[4:5], exec
	s_or_b64 s[0:1], s[0:1], s[4:5]
	s_mov_b32 s54, s62
	s_mov_b32 s5, s13
	s_and_saveexec_b64 s[76:77], s[0:1]
	s_cbranch_execz .LBB0_424
.LBB0_440:
	s_and_b32 s4, s56, 0xc000
	v_or_b32_e32 v38, s4, v110
	v_or_b32_e32 v204, s4, v111
	v_or_b32_e32 v205, s4, v112
	v_or_b32_e32 v248, s4, v113
	ds_read_b128 v[196:199], v38
	ds_read_b128 v[200:203], v204
	ds_read_b128 v[232:235], v38 offset:4096
	ds_read_b128 v[236:239], v204 offset:4096
	ds_read_b128 v[240:243], v205
	s_andn2_b64 vcc, exec, s[10:11]
	s_waitcnt lgkmcnt(4)
	v_mfma_f32_32x32x16_bf16 v[50:65], v[196:199], v[82:85], 0
	ds_read_b128 v[244:247], v205 offset:4096
	s_waitcnt lgkmcnt(4)
	v_mfma_f32_32x32x16_bf16 v[50:65], v[200:203], v[86:89], v[50:65]
	ds_read_b128 v[196:199], v248
	s_waitcnt lgkmcnt(4)
	v_mfma_f32_32x32x16_bf16 v[34:49], v[232:235], v[82:85], 0
	ds_read_b128 v[200:203], v248 offset:4096
	s_waitcnt lgkmcnt(4)
	v_mfma_f32_32x32x16_bf16 v[34:49], v[236:239], v[86:89], v[34:49]
	s_waitcnt lgkmcnt(3)
	v_mfma_f32_32x32x16_bf16 v[50:65], v[240:243], v[90:93], v[50:65]
	s_waitcnt lgkmcnt(2)
	v_mfma_f32_32x32x16_bf16 v[34:49], v[244:247], v[90:93], v[34:49]
	s_waitcnt lgkmcnt(1)
	v_mfma_f32_32x32x16_bf16 v[50:65], v[196:199], v[94:97], v[50:65]
	s_waitcnt lgkmcnt(0)
	v_mfma_f32_32x32x16_bf16 v[34:49], v[200:203], v[94:97], v[34:49]
	s_nop 1
	s_cbranch_vccnz .LBB0_474
	s_lshl_b32 s0, s5, 6
	s_sub_i32 s1, s54, s57
	s_add_i32 s0, s1, s0
	s_addk_i32 s0, 0xf000
	s_ashr_i32 s0, s0, 6
	v_sub_u32_e32 v66, s0, v105
	s_movk_i32 s0, 0x7c
	v_mul_lo_u32 v66, v66, s0
	v_add_u32_e32 v117, v114, v66
	ds_read_b32 v116, v117 offset:1056
	v_mov_b32_e32 v67, 0xff800000
	v_mov_b32_e32 v66, 0xff800000
	s_and_saveexec_b64 s[0:1], s[40:41]
	s_cbranch_execz .LBB0_443
	ds_read_b32 v66, v117 offset:928
	s_waitcnt lgkmcnt(0)
	v_add_f32_e32 v66, v50, v66

.LBB0_473:
	s_or_b64 exec, exec, s[0:1]
	v_readlane_b32 s0, v254, 61
	s_waitcnt lgkmcnt(12)
	v_add_f32_e32 v37, v37, v52
	v_readlane_b32 s1, v254, 62
	s_waitcnt lgkmcnt(11)
	v_add_f32_e32 v38, v38, v53
	s_waitcnt lgkmcnt(10)
	v_add_f32_e32 v39, v39, v54
	v_cndmask_b32_e64 v37, v215, v37, s[0:1]
	v_readlane_b32 s0, v255, 1
	v_readlane_b32 s1, v255, 2
	s_waitcnt lgkmcnt(9)
	v_add_f32_e32 v40, v40, v55
	s_waitcnt lgkmcnt(8)
	v_add_f32_e32 v41, v41, v56
	v_cndmask_b32_e64 v38, v215, v38, s[0:1]
	v_readlane_b32 s0, v255, 5
	v_readlane_b32 s1, v255, 6
	s_waitcnt lgkmcnt(7)
	v_add_f32_e32 v42, v42, v57
	s_waitcnt lgkmcnt(6)
	v_add_f32_e32 v43, v43, v58
	v_cndmask_b32_e64 v39, v215, v39, s[0:1]
	v_readlane_b32 s0, v255, 9
	v_readlane_b32 s1, v255, 10
	s_waitcnt lgkmcnt(5)
	v_add_f32_e32 v44, v44, v59
	s_waitcnt lgkmcnt(4)
	v_add_f32_e32 v45, v45, v60
	v_cndmask_b32_e64 v40, v215, v40, s[0:1]
	v_readlane_b32 s0, v255, 13
	v_readlane_b32 s1, v255, 14
	s_waitcnt lgkmcnt(3)
	v_add_f32_e32 v46, v46, v61
	v_add_f32_e32 v34, v34, v116
	v_cndmask_b32_e64 v41, v215, v41, s[0:1]
	v_readlane_b32 s0, v255, 17
	v_readlane_b32 s1, v255, 18
	v_add_f32_e32 v35, v35, v50
	v_add_f32_e32 v36, v36, v51
	v_cndmask_b32_e64 v42, v215, v42, s[0:1]
	v_readlane_b32 s0, v255, 21
	v_readlane_b32 s1, v255, 22
	s_waitcnt lgkmcnt(2)
	v_add_f32_e32 v47, v47, v62
	s_waitcnt lgkmcnt(1)
	v_add_f32_e32 v48, v48, v118
	v_cndmask_b32_e64 v43, v215, v43, s[0:1]
	v_readlane_b32 s0, v255, 25
	v_readlane_b32 s1, v255, 26
	s_waitcnt lgkmcnt(0)
	v_add_f32_e32 v49, v49, v63
	v_mov_b64_e32 v[50:51], v[66:67]
	v_cndmask_b32_e64 v44, v215, v44, s[0:1]
	v_readlane_b32 s0, v255, 29
	v_readlane_b32 s1, v255, 30
	v_cndmask_b32_e64 v34, v215, v34, s[42:43]
	v_cndmask_b32_e64 v35, v215, v35, s[46:47]
	v_cndmask_b32_e64 v45, v215, v45, s[0:1]
	v_readlane_b32 s0, v255, 33
	v_readlane_b32 s1, v255, 34
	v_cndmask_b32_e64 v36, v215, v36, s[50:51]
	v_cndmask_b32_e64 v48, v215, v48, s[16:17]
	v_cndmask_b32_e64 v46, v215, v46, s[0:1]
	v_readlane_b32 s0, v255, 37
	v_readlane_b32 s1, v255, 38
	v_cndmask_b32_e64 v49, v215, v49, s[72:73]
	v_mov_b64_e32 v[52:53], v[68:69]
	v_cndmask_b32_e64 v47, v215, v47, s[0:1]
	v_mov_b64_e32 v[54:55], v[70:71]
	v_mov_b64_e32 v[56:57], v[72:73]
	v_mov_b64_e32 v[58:59], v[74:75]
	v_mov_b64_e32 v[60:61], v[76:77]
	v_mov_b64_e32 v[62:63], v[78:79]
	v_mov_b64_e32 v[64:65], v[80:81]
.LBB0_474:
	s_nop 10
	s_nop 7
	s_nop 4
	v_max3_f32 v66, v34, v35, v36
	v_max3_f32 v67, v50, v51, v52
	v_max3_f32 v66, v66, v37, v38
	v_max3_f32 v67, v67, v53, v54
	v_max3_f32 v66, v66, v39, v40
	v_max3_f32 v67, v67, v55, v56
	v_max3_f32 v66, v66, v41, v42
	v_max3_f32 v67, v67, v57, v58
	v_max3_f32 v66, v66, v43, v44
	v_max3_f32 v67, v67, v59, v60
	v_max3_f32 v66, v66, v45, v46
	v_max3_f32 v67, v67, v61, v62
	v_max3_f32 v66, v66, v47, v48
	v_max3_f32 v67, v67, v63, v64
	v_max3_f32 v67, v67, v65, v49
	v_max_f32_e32 v66, v66, v67
	v_and_b32_e32 v68, 64, v221
	v_xor_b32_e32 v67, 32, v221
	v_add_u32_e32 v68, 64, v68
	v_cmp_lt_i32_e32 vcc, v67, v68
	s_nop 1
	v_cndmask_b32_e32 v67, v221, v67, vcc
	v_lshlrev_b32_e32 v70, 2, v67
	ds_bpermute_b32 v67, v70, v66
	s_waitcnt lgkmcnt(0)
	v_max3_f32 v66, v0, v66, v67
	v_sub_f32_e32 v50, v50, v66
	v_sub_f32_e32 v34, v34, v66
	v_exp_f32_e32 v50, v50
	v_exp_f32_e32 v34, v34
	v_sub_f32_e32 v51, v51, v66
	v_sub_f32_e32 v35, v35, v66
	v_exp_f32_e32 v51, v51
	v_exp_f32_e32 v35, v35
	v_sub_f32_e32 v52, v52, v66
	v_sub_f32_e32 v36, v36, v66
	v_exp_f32_e32 v52, v52
	v_exp_f32_e32 v36, v36
	v_add_f32_e32 v67, v50, v34
	v_sub_f32_e32 v53, v53, v66
	v_sub_f32_e32 v37, v37, v66
	v_add_f32_e32 v67, 0, v67
	v_add_f32_e32 v68, v51, v35
	v_exp_f32_e32 v53, v53
	v_exp_f32_e32 v37, v37
	v_add_f32_e32 v67, v68, v67
	v_add_f32_e32 v68, v52, v36
	v_sub_f32_e32 v38, v38, v66
	v_add_f32_e32 v69, v68, v67
	v_sub_f32_e32 v54, v54, v66
	v_exp_f32_e32 v67, v38
	v_sub_f32_e32 v38, v55, v66
	v_exp_f32_e32 v54, v54
	v_exp_f32_e32 v55, v38
	v_sub_f32_e32 v38, v39, v66
	v_add_f32_e32 v71, v53, v37
	v_exp_f32_e32 v68, v38
	v_sub_f32_e32 v56, v56, v66
	v_sub_f32_e32 v40, v40, v66
	v_add_f32_e32 v38, v71, v69
	v_exp_f32_e32 v56, v56
	v_exp_f32_e32 v69, v40
	v_add_f32_e32 v39, v54, v67
	v_add_f32_e32 v38, v39, v38
	v_add_f32_e32 v39, v55, v68
	v_sub_f32_e32 v40, v57, v66
	v_exp_f32_e32 v57, v40
	v_sub_f32_e32 v40, v41, v66
	v_add_f32_e32 v38, v39, v38
	v_add_f32_e32 v39, v56, v69
	v_exp_f32_e32 v41, v40
	v_add_f32_e32 v71, v39, v38
	v_sub_f32_e32 v38, v58, v66
	v_sub_f32_e32 v39, v42, v66
	v_exp_f32_e32 v38, v38
	v_exp_f32_e32 v39, v39
	v_add_f32_e32 v72, v57, v41
	v_sub_f32_e32 v40, v59, v66
	v_sub_f32_e32 v42, v43, v66
	v_add_f32_e32 v43, v72, v71
	v_add_f32_e32 v58, v38, v39
	v_exp_f32_e32 v40, v40
	v_exp_f32_e32 v42, v42
	v_add_f32_e32 v59, v58, v43
	v_sub_f32_e32 v43, v60, v66
	v_sub_f32_e32 v44, v44, v66
	v_exp_f32_e32 v43, v43
	v_exp_f32_e32 v44, v44
	v_add_f32_e32 v71, v40, v42
	v_sub_f32_e32 v58, v61, v66
	v_sub_f32_e32 v45, v45, v66
	v_add_f32_e32 v59, v71, v59
	v_add_f32_e32 v60, v43, v44
	v_exp_f32_e32 v58, v58
	v_exp_f32_e32 v45, v45
	v_add_f32_e32 v61, v60, v59
	v_sub_f32_e32 v59, v62, v66
	v_sub_f32_e32 v46, v46, v66
	v_exp_f32_e32 v59, v59
	v_exp_f32_e32 v46, v46
	v_add_f32_e32 v71, v58, v45
	v_sub_f32_e32 v60, v63, v66
	v_sub_f32_e32 v47, v47, v66
	v_add_f32_e32 v61, v71, v61
	v_add_f32_e32 v62, v59, v46
	v_exp_f32_e32 v60, v60
	v_exp_f32_e32 v47, v47
	v_add_f32_e32 v63, v62, v61
	v_sub_f32_e32 v61, v64, v66
	v_sub_f32_e32 v48, v48, v66
	v_exp_f32_e32 v61, v61
	v_exp_f32_e32 v48, v48
	v_sub_f32_e32 v62, v65, v66
	v_sub_f32_e32 v49, v49, v66
	v_exp_f32_e32 v62, v62
	v_exp_f32_e32 v49, v49
	v_add_f32_e32 v71, v60, v47
	v_add_f32_e32 v63, v71, v63
	v_add_f32_e32 v64, v61, v48
	v_add_f32_e32 v63, v64, v63
	v_add_f32_e32 v64, v62, v49
	v_sub_f32_e32 v0, v0, v66
	v_add_f32_e32 v63, v64, v63
	v_exp_f32_e32 v0, v0
	ds_bpermute_b32 v64, v70, v63
	v_cmp_neq_f32_e32 vcc, 1.0, v0
	s_cbranch_vccz .LBB0_423
	v_pk_mul_f32 v[16:17], v[16:17], v[0:1] op_sel_hi:[1,0]
	v_pk_mul_f32 v[14:15], v[14:15], v[0:1] op_sel_hi:[1,0]
	v_pk_mul_f32 v[12:13], v[12:13], v[0:1] op_sel_hi:[1,0]
	v_pk_mul_f32 v[10:11], v[10:11], v[0:1] op_sel_hi:[1,0]
	v_pk_mul_f32 v[8:9], v[8:9], v[0:1] op_sel_hi:[1,0]
	v_pk_mul_f32 v[6:7], v[6:7], v[0:1] op_sel_hi:[1,0]
	v_pk_mul_f32 v[4:5], v[4:5], v[0:1] op_sel_hi:[1,0]
	v_pk_mul_f32 v[2:3], v[2:3], v[0:1] op_sel_hi:[1,0]
	v_pk_mul_f32 v[32:33], v[32:33], v[0:1] op_sel_hi:[1,0]
	v_pk_mul_f32 v[30:31], v[30:31], v[0:1] op_sel_hi:[1,0]
	v_pk_mul_f32 v[28:29], v[28:29], v[0:1] op_sel_hi:[1,0]
	v_pk_mul_f32 v[26:27], v[26:27], v[0:1] op_sel_hi:[1,0]
	v_pk_mul_f32 v[24:25], v[24:25], v[0:1] op_sel_hi:[1,0]
	v_pk_mul_f32 v[22:23], v[22:23], v[0:1] op_sel_hi:[1,0]
	v_pk_mul_f32 v[20:21], v[20:21], v[0:1] op_sel_hi:[1,0]
	v_pk_mul_f32 v[18:19], v[18:19], v[0:1] op_sel_hi:[1,0]
	s_branch .LBB0_423

.LBB0_518:
	s_mul_i32 s0, s12, 0xa000
	v_add_u32_e32 v187, s0, v178
	v_add_u32_e32 v189, s0, v180
	v_add_u32_e32 v194, s0, v182
	v_add_u32_e32 v195, s0, v184
	ds_read_b128 v[196:199], v187
	ds_read_b128 v[200:203], v189
	ds_read_b128 v[232:235], v187 offset:12288
	ds_read_b128 v[236:239], v189 offset:12288
	ds_read_b128 v[240:243], v194
	s_waitcnt lgkmcnt(4)
	v_mfma_f32_32x32x16_bf16 v[66:81], v[196:199], v[98:101], 0
	ds_read_b128 v[244:247], v194 offset:12288
	s_waitcnt lgkmcnt(4)
	v_mfma_f32_32x32x16_bf16 v[66:81], v[200:203], v[102:105], v[66:81]
	ds_read_b128 v[196:199], v195
	s_waitcnt lgkmcnt(4)
	v_mfma_f32_32x32x16_bf16 v[82:97], v[232:235], v[98:101], 0
	ds_read_b128 v[200:203], v195 offset:12288
	s_waitcnt lgkmcnt(4)
	v_mfma_f32_32x32x16_bf16 v[82:97], v[236:239], v[102:105], v[82:97]
	ds_read_b128 v[232:235], v187 offset:128
	s_waitcnt lgkmcnt(4)
	v_mfma_f32_32x32x16_bf16 v[66:81], v[240:243], v[106:109], v[66:81]
	ds_read_b128 v[236:239], v187 offset:12416
	s_waitcnt lgkmcnt(4)
	v_mfma_f32_32x32x16_bf16 v[82:97], v[244:247], v[106:109], v[82:97]
	ds_read_b128 v[240:243], v189 offset:128
	s_waitcnt lgkmcnt(4)
	v_mfma_f32_32x32x16_bf16 v[66:81], v[196:199], v[110:113], v[66:81]
	ds_read_b128 v[244:247], v189 offset:12416
	s_waitcnt lgkmcnt(4)
	v_mfma_f32_32x32x16_bf16 v[82:97], v[200:203], v[110:113], v[82:97]
	ds_read_b128 v[196:199], v194 offset:128
	s_waitcnt lgkmcnt(4)
	v_mfma_f32_32x32x16_bf16 v[66:81], v[232:235], v[114:117], v[66:81]
	ds_read_b128 v[200:203], v194 offset:12416
	s_waitcnt lgkmcnt(4)
	v_mfma_f32_32x32x16_bf16 v[82:97], v[236:239], v[114:117], v[82:97]
	ds_read_b128 v[232:235], v195 offset:128
	s_waitcnt lgkmcnt(4)
	v_mfma_f32_32x32x16_bf16 v[66:81], v[240:243], v[118:121], v[66:81]
	ds_read_b128 v[236:239], v195 offset:12416
	s_waitcnt lgkmcnt(4)
	v_mfma_f32_32x32x16_bf16 v[82:97], v[244:247], v[118:121], v[82:97]
	ds_read_b128 v[240:243], v187 offset:256
	s_waitcnt lgkmcnt(4)
	v_mfma_f32_32x32x16_bf16 v[66:81], v[196:199], v[122:125], v[66:81]
	ds_read_b128 v[244:247], v187 offset:12544
	s_waitcnt lgkmcnt(4)
	v_mfma_f32_32x32x16_bf16 v[82:97], v[200:203], v[122:125], v[82:97]
	ds_read_b128 v[196:199], v189 offset:256
	s_waitcnt lgkmcnt(4)
	v_mfma_f32_32x32x16_bf16 v[66:81], v[232:235], v[126:129], v[66:81]
	ds_read_b128 v[200:203], v189 offset:12544
	s_waitcnt lgkmcnt(4)
	v_mfma_f32_32x32x16_bf16 v[82:97], v[236:239], v[126:129], v[82:97]
	ds_read_b128 v[232:235], v194 offset:256
	s_waitcnt lgkmcnt(4)
	v_mfma_f32_32x32x16_bf16 v[66:81], v[240:243], v[130:133], v[66:81]
	ds_read_b128 v[236:239], v194 offset:12544
	s_waitcnt lgkmcnt(4)
	v_mfma_f32_32x32x16_bf16 v[82:97], v[244:247], v[130:133], v[82:97]
	ds_read_b128 v[240:243], v195 offset:12544
	s_waitcnt lgkmcnt(4)
	v_mfma_f32_32x32x16_bf16 v[66:81], v[196:199], v[134:137], v[66:81]
	ds_read_b128 v[244:247], v195 offset:256
	s_waitcnt lgkmcnt(4)
	v_mfma_f32_32x32x16_bf16 v[82:97], v[200:203], v[134:137], v[82:97]
	s_waitcnt lgkmcnt(3)
	v_mfma_f32_32x32x16_bf16 v[66:81], v[232:235], v[138:141], v[66:81]
	s_waitcnt lgkmcnt(2)
	v_mfma_f32_32x32x16_bf16 v[82:97], v[236:239], v[138:141], v[82:97]
	s_waitcnt lgkmcnt(1)
	v_mfma_f32_32x32x16_bf16 v[82:97], v[240:243], v[142:145], v[82:97]
	s_waitcnt lgkmcnt(0)
	v_mfma_f32_32x32x16_bf16 v[66:81], v[244:247], v[142:145], v[66:81]
	s_nop 1
	s_nop 8
	s_nop 7
	s_nop 4
	v_max3_f32 v187, v82, v83, v84
	v_max3_f32 v189, v66, v67, v68
	v_max3_f32 v187, v187, v85, v86
	v_max3_f32 v189, v189, v69, v70
	v_max3_f32 v187, v187, v87, v88
	v_max3_f32 v189, v189, v71, v72
	v_max3_f32 v187, v187, v89, v90
	v_max3_f32 v189, v189, v73, v74
	v_max3_f32 v187, v187, v91, v92
	v_max3_f32 v189, v189, v75, v76
	v_max3_f32 v187, v187, v93, v94
	v_max3_f32 v189, v189, v77, v78
	v_max3_f32 v187, v187, v95, v96
	v_max3_f32 v189, v189, v79, v80
	v_max3_f32 v189, v189, v81, v97
	v_max_f32_e32 v187, v187, v189
	v_and_b32_e32 v190, 64, v221
	v_xor_b32_e32 v189, 32, v221
	v_add_u32_e32 v190, 64, v190
	v_cmp_lt_i32_e32 vcc, v189, v190
	s_nop 1
	v_cndmask_b32_e32 v189, v221, v189, vcc
	v_lshlrev_b32_e32 v195, 2, v189
	ds_bpermute_b32 v189, v195, v187
	s_waitcnt lgkmcnt(0)
	v_max3_f32 v187, v188, v187, v189
	v_sub_f32_e32 v66, v66, v187
	v_exp_f32_e32 v189, v66
	v_sub_f32_e32 v66, v82, v187
	v_exp_f32_e32 v190, v66
	v_sub_f32_e32 v66, v67, v187
	v_exp_f32_e32 v67, v66
	v_sub_f32_e32 v66, v83, v187
	v_exp_f32_e32 v83, v66
	v_sub_f32_e32 v68, v68, v187
	v_sub_f32_e32 v84, v84, v187
	v_exp_f32_e32 v68, v68
	v_exp_f32_e32 v84, v84
	v_add_f32_e32 v82, v189, v190
	v_sub_f32_e32 v69, v69, v187
	v_sub_f32_e32 v85, v85, v187
	v_sub_f32_e32 v66, v188, v187
	v_add_f32_e32 v82, 0, v82
	v_add_f32_e32 v188, v67, v83
	v_exp_f32_e32 v69, v69
	v_exp_f32_e32 v85, v85
	v_add_f32_e32 v82, v188, v82
	v_add_f32_e32 v188, v68, v84
	v_sub_f32_e32 v70, v70, v187
	v_add_f32_e32 v82, v188, v82
	v_exp_f32_e32 v188, v70
	v_sub_f32_e32 v70, v86, v187
	v_exp_f32_e32 v86, v70
	v_sub_f32_e32 v70, v71, v187
	v_add_f32_e32 v192, v69, v85
	v_exp_f32_e32 v191, v70
	v_sub_f32_e32 v70, v87, v187
	v_sub_f32_e32 v72, v72, v187
	v_exp_f32_e32 v87, v70
	v_add_f32_e32 v70, v192, v82
	v_exp_f32_e32 v192, v72
	v_sub_f32_e32 v72, v88, v187
	v_exp_f32_e32 v88, v72
	v_add_f32_e32 v71, v188, v86
	v_add_f32_e32 v70, v71, v70
	v_add_f32_e32 v71, v191, v87
	v_sub_f32_e32 v72, v73, v187
	v_exp_f32_e32 v73, v72
	v_sub_f32_e32 v72, v89, v187
	v_add_f32_e32 v70, v71, v70
	v_add_f32_e32 v71, v192, v88
	v_exp_f32_e32 v89, v72
	v_add_f32_e32 v82, v71, v70
	v_sub_f32_e32 v70, v74, v187
	v_sub_f32_e32 v71, v90, v187
	v_exp_f32_e32 v70, v70
	v_exp_f32_e32 v71, v71
	v_sub_f32_e32 v72, v75, v187
	v_sub_f32_e32 v74, v91, v187
	v_exp_f32_e32 v72, v72
	v_exp_f32_e32 v75, v74
	v_sub_f32_e32 v76, v76, v187
	v_sub_f32_e32 v90, v92, v187
	v_sub_f32_e32 v78, v78, v187
	v_exp_f32_e32 v76, v76
	v_exp_f32_e32 v90, v90
	v_sub_f32_e32 v77, v77, v187
	v_sub_f32_e32 v91, v93, v187
	v_exp_f32_e32 v92, v78
	v_sub_f32_e32 v78, v94, v187
	v_add_f32_e32 v193, v73, v89
	v_exp_f32_e32 v77, v77
	v_exp_f32_e32 v91, v91
	v_exp_f32_e32 v93, v78
	v_sub_f32_e32 v78, v79, v187
	v_sub_f32_e32 v79, v80, v187
	v_add_f32_e32 v74, v193, v82
	v_add_f32_e32 v82, v70, v71
	v_exp_f32_e32 v94, v78
	v_sub_f32_e32 v78, v95, v187
	v_exp_f32_e32 v193, v79
	v_sub_f32_e32 v79, v96, v187
	v_add_f32_e32 v74, v82, v74
	v_add_f32_e32 v82, v72, v75
	v_exp_f32_e32 v95, v78
	v_exp_f32_e32 v96, v79
	v_sub_f32_e32 v79, v81, v187
	v_add_f32_e32 v74, v82, v74
	v_add_f32_e32 v82, v76, v90
	v_exp_f32_e32 v194, v79
	v_sub_f32_e32 v79, v97, v187
	v_add_f32_e32 v74, v82, v74
	v_add_f32_e32 v82, v77, v91
	v_exp_f32_e32 v97, v79
	v_add_f32_e32 v74, v82, v74
	v_add_f32_e32 v78, v92, v93
	v_add_f32_e32 v74, v78, v74
	v_add_f32_e32 v78, v94, v95
	v_add_f32_e32 v74, v78, v74
	v_add_f32_e32 v78, v193, v96
	v_add_f32_e32 v74, v78, v74
	v_add_f32_e32 v78, v194, v97
	v_add_f32_e32 v74, v78, v74
	v_exp_f32_e32 v66, v66
	ds_bpermute_b32 v78, v195, v74
	v_cmp_neq_f32_e32 vcc, 1.0, v66
	s_cbranch_vccz .LBB0_520
	v_pk_mul_f32 v[64:65], v[64:65], v[66:67] op_sel_hi:[1,0]
	v_pk_mul_f32 v[62:63], v[62:63], v[66:67] op_sel_hi:[1,0]
	v_pk_mul_f32 v[60:61], v[60:61], v[66:67] op_sel_hi:[1,0]
	v_pk_mul_f32 v[58:59], v[58:59], v[66:67] op_sel_hi:[1,0]
	v_pk_mul_f32 v[56:57], v[56:57], v[66:67] op_sel_hi:[1,0]
	v_pk_mul_f32 v[54:55], v[54:55], v[66:67] op_sel_hi:[1,0]
	v_pk_mul_f32 v[52:53], v[52:53], v[66:67] op_sel_hi:[1,0]
	v_pk_mul_f32 v[50:51], v[50:51], v[66:67] op_sel_hi:[1,0]
	v_pk_mul_f32 v[48:49], v[48:49], v[66:67] op_sel_hi:[1,0]
	v_pk_mul_f32 v[46:47], v[46:47], v[66:67] op_sel_hi:[1,0]
	v_pk_mul_f32 v[44:45], v[44:45], v[66:67] op_sel_hi:[1,0]
	v_pk_mul_f32 v[42:43], v[42:43], v[66:67] op_sel_hi:[1,0]
	v_pk_mul_f32 v[40:41], v[40:41], v[66:67] op_sel_hi:[1,0]
	v_pk_mul_f32 v[38:39], v[38:39], v[66:67] op_sel_hi:[1,0]
	v_pk_mul_f32 v[36:37], v[36:37], v[66:67] op_sel_hi:[1,0]
	v_pk_mul_f32 v[34:35], v[34:35], v[66:67] op_sel_hi:[1,0]
	v_pk_mul_f32 v[32:33], v[32:33], v[66:67] op_sel_hi:[1,0]
	v_pk_mul_f32 v[30:31], v[30:31], v[66:67] op_sel_hi:[1,0]
	v_pk_mul_f32 v[28:29], v[28:29], v[66:67] op_sel_hi:[1,0]
	v_pk_mul_f32 v[26:27], v[26:27], v[66:67] op_sel_hi:[1,0]
	v_pk_mul_f32 v[24:25], v[24:25], v[66:67] op_sel_hi:[1,0]
	v_pk_mul_f32 v[22:23], v[22:23], v[66:67] op_sel_hi:[1,0]
	v_pk_mul_f32 v[20:21], v[20:21], v[66:67] op_sel_hi:[1,0]
	v_pk_mul_f32 v[18:19], v[18:19], v[66:67] op_sel_hi:[1,0]
	v_pk_mul_f32 v[16:17], v[16:17], v[66:67] op_sel_hi:[1,0]
	v_pk_mul_f32 v[14:15], v[14:15], v[66:67] op_sel_hi:[1,0]
	v_pk_mul_f32 v[12:13], v[12:13], v[66:67] op_sel_hi:[1,0]
	v_pk_mul_f32 v[10:11], v[10:11], v[66:67] op_sel_hi:[1,0]
	v_pk_mul_f32 v[8:9], v[8:9], v[66:67] op_sel_hi:[1,0]
	v_pk_mul_f32 v[6:7], v[6:7], v[66:67] op_sel_hi:[1,0]
	v_pk_mul_f32 v[4:5], v[4:5], v[66:67] op_sel_hi:[1,0]
	v_pk_mul_f32 v[2:3], v[2:3], v[66:67] op_sel_hi:[1,0]
